# GEMM prologues: second K-tile's loads issued before the first tile's wait and barrier
# baseline (speedup 1.0000x reference)
; #define PG8_STAGE(bufoff, gbase, voff) do { _Pragma("unroll") for (int _i = 0; _i < 2; ++_i) \
;         __builtin_amdgcn_global_load_lds((const unsigned*)((const char*)(gbase) + (voff)[_i]), (PG8_LAS unsigned*)(lds + (bufoff) + ldsw + _i * 8192), 16, 0, 0); } while (0)
; #define PG8_WAIT_V(n) asm volatile("s_waitcnt vmcnt(" #n ")" ::: "memory")
; #define PG8_BAR __builtin_amdgcn_s_barrier()
;     __device__ bool next(int i, pg8::Unit& u) const { if (i != 0 || !valid) return false; u.pm = pm; u.pn = pn; return true; }
; template <class Epi, class Sched, bool STAMP = false>
; __device__ __forceinline__ void gemm_phase(PG8_LAS unsigned char* lds, const Gemm g, const Sched& S, const Epi& E, unsigned long long* stamps) {
;     ...
;     for (int i = 0; i < 2; ++i) { int R, C; stage_rc(tid * 16 + i * 8192, R, C); const int Rb = Epi::PERM ? ((R & ~31) + perm32(R & 31)) : R;
;         voffA[i] = (unsigned)(R * LD + C) * 2u; voffB[i] = (unsigned)(Rb * LD + C) * 2u; }
;     const size_t kstep = (size_t)(BK * 2);
;     const size_t hstep = (size_t)HALF * LD * 2;
;     const size_t tstep = 2 * hstep;
;     const unsigned ldsw = (unsigned)wid * 1024u;
;     const int aoff = lds_byte(wr * 64 + fr, fq * 8), boff = lds_byte(wc * 32 + fr, fq * 8);
;     ...
;     Unit cur, nxt; int ui = 0;
;     if (!S.next(0, cur)) return;
;     f32x4 acc[2][2][4][2];
; #pragma unroll
;     for (int a = 0; a < 2; ++a)
; #pragma unroll
;         for (int b = 0; b < 2; ++b)
; #pragma unroll
;             for (int m = 0; m < 4; ++m)
; #pragma unroll
;                 for (int n = 0; n < 2; ++n) acc[a][b][m][n] = (f32x4){0.f, 0.f, 0.f, 0.f};
;     bf16x8 At[4][2], B0[2][2], B1[2][2];
;     const char* cA = (const char*)g.A + (size_t)cur.pm * tstep; const char* cB = (const char*)g.Bt + (size_t)cur.pn * tstep;
;     S.a_ready(cur);
;     PG8_STAGE(PG8_SB(0, 0), cB, voffB); PG8_STAGE(PG8_SA(0, 0), cA, voffA); PG8_STAGE(PG8_SB(0, 1), cB + hstep, voffB); PG8_STAGE(PG8_SA(0, 1), cA + hstep, voffA);
;     if (wr == 1) PG8_BAR;
;     PG8_WAIT_V(4); PG8_BAR;
;     PG8_STAGE(PG8_SB(1, 0), cB + kstep, voffB); PG8_STAGE(PG8_SA(1, 0), cA + kstep, voffA); PG8_STAGE(PG8_SB(1, 1), cB + hstep + kstep, voffB);
;     PG8_WAIT_V(6); PG8_BAR;
.LBB0_40:
	s_sext_i32_i8 s56, s0
	s_and_b64 s[0:1], s[34:35], exec
	s_mov_b32 s0, 0x33000
	s_cselect_b32 s0, s0, 0x11000
	s_add_u32 s0, s2, s0
	s_addc_u32 s1, s3, 0
	s_add_u32 s0, s0, 0x2060000
	s_addc_u32 s1, s1, 0
	s_add_u32 s2, s2, 0x5500000
	v_lshrrev_b32_e32 v16, 1, v14
	s_addc_u32 s3, s3, 0
	v_and_b32_e32 v16, 24, v16
	s_lshl_b32 s4, s4, 5
	v_and_b32_e32 v15, 15, v14
	v_lshlrev_b32_e32 v17, 1, v16
	v_lshlrev_b32_e32 v14, 2, v14
	s_and_b32 s6, s4, 0x60
	s_add_i32 m0, s23, 0x18000
	v_lshl_add_u64 v[6:7], v[6:7], 0, s[18:19]
	v_lshl_or_b32 v139, s5, 6, v15
	v_lshl_or_b32 v15, v15, 6, v17
	s_lshl_b32 s5, s5, 13
	v_and_b32_e32 v14, 32, v14
	s_lshl_b32 s4, s6, 7
	s_nop 0
	global_load_lds_dwordx4 v[6:7], off
	v_lshl_add_u64 v[4:5], v[4:5], 0, s[18:19]
	s_add_i32 m0, s23, 0x1a000
	s_add_i32 s49, s23, 0x8000
	s_add_i32 s53, s23, 0xa000
	v_bitop3_b32 v166, v15, s4, v14 bitop3:0xde
	global_load_lds_dwordx4 v[4:5], off
	v_lshl_add_u64 v[2:3], v[2:3], 0, s[18:19]
	s_mov_b32 m0, s49
	s_add_u32 s4, s26, 0x40080
	v_bitop3_b32 v17, v15, s5, v14 bitop3:0xde
	global_load_lds_dwordx4 v[2:3], off
	v_lshl_add_u64 v[0:1], v[0:1], 0, s[18:19]
	s_mov_b32 m0, s53
	s_addc_u32 s5, s27, 0
	global_load_lds_dwordx4 v[0:1], off
	s_add_i32 m0, s23, 0x1c000
	v_lshl_add_u64 v[0:1], s[4:5], 0, v[128:129]
	global_load_lds_dwordx4 v[0:1], off
	v_lshl_add_u64 v[0:1], s[4:5], 0, v[148:149]
	s_add_i32 m0, s23, 0x1e000
	s_mov_b32 s48, 0
	global_load_lds_dwordx4 v[0:1], off
	v_lshlrev_b32_e32 v0, 14, v12
	v_and_b32_e32 v0, 0xffff8000, v0
	v_lshl_add_u32 v0, v11, 11, v0
	v_and_b32_e32 v1, 1, v12
	v_lshl_or_b32 v0, v1, 6, v0
	v_lshl_add_u32 v154, v13, 1, v0
	v_lshlrev_b32_e32 v0, 14, v8
	v_and_b32_e32 v0, 0xffff8000, v0
	s_waitcnt vmcnt(10)
	s_barrier
	s_waitcnt vmcnt(6)
	v_lshl_add_u32 v0, v9, 11, v0
	v_and_b32_e32 v1, 1, v8
	v_lshl_or_b32 v0, v1, 6, v0
	v_or_b32_e32 v167, s6, v16
	v_mov_b32_e32 v155, v129
	v_lshl_add_u32 v156, v10, 1, v0
	v_mov_b32_e32 v157, v129
	v_add_u32_e32 v168, 0, v17
	s_barrier

; #define PG8_STAGE(bufoff, gbase, voff) do { _Pragma("unroll") for (int _i = 0; _i < 2; ++_i) \
;         __builtin_amdgcn_global_load_lds((const unsigned*)((const char*)(gbase) + (voff)[_i]), (PG8_LAS unsigned*)(lds + (bufoff) + ldsw + _i * 8192), 16, 0, 0); } while (0)
; #define PG8_WAIT_V(n) asm volatile("s_waitcnt vmcnt(" #n ")" ::: "memory")
; #define PG8_BAR __builtin_amdgcn_s_barrier()
;     __device__ bool next(int i, pg8::Unit& u) const { if (i != 0 || !valid) return false; u.pm = pm; u.pn = pn; return true; }
; template <class Epi, class Sched, bool STAMP = false>
; __device__ __forceinline__ void gemm_phase(PG8_LAS unsigned char* lds, const Gemm g, const Sched& S, const Epi& E, unsigned long long* stamps) {
;     ...
;     for (int i = 0; i < 2; ++i) { int R, C; stage_rc(tid * 16 + i * 8192, R, C); const int Rb = Epi::PERM ? ((R & ~31) + perm32(R & 31)) : R;
;         voffA[i] = (unsigned)(R * LD + C) * 2u; voffB[i] = (unsigned)(Rb * LD + C) * 2u; }
;     const size_t kstep = (size_t)(BK * 2);
;     const size_t hstep = (size_t)HALF * LD * 2;
;     const size_t tstep = 2 * hstep;
;     const unsigned ldsw = (unsigned)wid * 1024u;
;     const int aoff = lds_byte(wr * 64 + fr, fq * 8), boff = lds_byte(wc * 32 + fr, fq * 8);
;     ...
;     Unit cur, nxt; int ui = 0;
;     if (!S.next(0, cur)) return;
;     f32x4 acc[2][2][4][2];
; #pragma unroll
;     for (int a = 0; a < 2; ++a)
; #pragma unroll
;         for (int b = 0; b < 2; ++b)
; #pragma unroll
;             for (int m = 0; m < 4; ++m)
; #pragma unroll
;                 for (int n = 0; n < 2; ++n) acc[a][b][m][n] = (f32x4){0.f, 0.f, 0.f, 0.f};
;     bf16x8 At[4][2], B0[2][2], B1[2][2];
;     const char* cA = (const char*)g.A + (size_t)cur.pm * tstep; const char* cB = (const char*)g.Bt + (size_t)cur.pn * tstep;
;     S.a_ready(cur);
;     PG8_STAGE(PG8_SB(0, 0), cB, voffB); PG8_STAGE(PG8_SA(0, 0), cA, voffA); PG8_STAGE(PG8_SB(0, 1), cB + hstep, voffB); PG8_STAGE(PG8_SA(0, 1), cA + hstep, voffA);
;     if (wr == 1) PG8_BAR;
;     PG8_WAIT_V(4); PG8_BAR;
;     PG8_STAGE(PG8_SB(1, 0), cB + kstep, voffB); PG8_STAGE(PG8_SA(1, 0), cA + kstep, voffA); PG8_STAGE(PG8_SB(1, 1), cB + hstep + kstep, voffB);
;     PG8_WAIT_V(6); PG8_BAR;
.LBB0_132:
	v_bfe_u32 v17, v9, 4, 2
	v_and_b32_e32 v18, 15, v9
	v_lshlrev_b32_e32 v19, 4, v17
	v_lshlrev_b32_e32 v9, 2, v9
	v_lshl_or_b32 v139, s6, 6, v18
	v_lshl_or_b32 v18, v18, 6, v19
	s_lshl_b32 s6, s6, 13
	v_and_b32_e32 v9, 32, v9
	v_bitop3_b32 v19, v18, s6, v9 bitop3:0xde
	s_lshl_b32 s6, s7, 5
	s_and_b32 s14, s6, 0x60
	s_lshl_b32 s6, s14, 7
	v_bitop3_b32 v166, v18, s6, v9 bitop3:0xde
	s_add_u32 s6, s10, 0x2200000
	s_addc_u32 s7, s46, 0
	s_add_i32 m0, s37, 0x18000
	v_lshl_add_u64 v[6:7], v[6:7], 0, s[18:19]
	s_nop 0
	global_load_lds_dwordx4 v[6:7], off
	v_lshl_add_u64 v[4:5], v[4:5], 0, s[18:19]
	s_add_i32 m0, s37, 0x1a000
	s_add_i32 s88, s37, 0x8000
	s_add_i32 s89, s37, 0xa000
	global_load_lds_dwordx4 v[4:5], off
	v_lshl_add_u64 v[2:3], v[2:3], 0, s[18:19]
	s_mov_b32 m0, s88
	s_add_u32 s12, s48, 0x40080
	global_load_lds_dwordx4 v[2:3], off
	v_lshl_add_u64 v[0:1], v[0:1], 0, s[18:19]
	s_mov_b32 m0, s89
	s_addc_u32 s13, s49, 0
	global_load_lds_dwordx4 v[0:1], off
	s_add_i32 m0, s37, 0x1c000
	v_lshl_add_u64 v[0:1], s[12:13], 0, v[148:149]
	global_load_lds_dwordx4 v[0:1], off
	v_lshl_add_u64 v[0:1], s[12:13], 0, v[150:151]
	s_add_i32 m0, s37, 0x1e000
	s_ashr_i32 s97, s47, 31
	global_load_lds_dwordx4 v[0:1], off
	v_lshlrev_b32_e32 v0, 13, v8
	v_and_b32_e32 v0, 0x7fffc000, v0
	v_lshl_add_u32 v0, v10, 10, v0
	v_or_b32_e32 v0, v0, v11
	v_add_lshl_u32 v128, v0, v12, 1
	v_lshlrev_b32_e32 v0, 13, v13
	v_and_b32_e32 v0, 0x7fffc000, v0
	v_lshl_add_u32 v0, v14, 10, v0
	s_waitcnt vmcnt(10)
	s_barrier
	s_waitcnt vmcnt(6)
	v_lshl_or_b32 v167, v17, 2, s14
	s_mov_b64 s[14:15], 0x40080
	v_or_b32_e32 v0, v0, v15
	s_cmp_lg_u64 s[0:1], 0
	v_lshl_add_u64 v[152:153], v[128:129], 0, s[14:15]
	v_add_lshl_u32 v128, v0, v16, 1
	s_mov_b32 s96, 0
	v_cmp_eq_u32_e64 s[40:41], 0, v17
	s_cselect_b64 s[12:13], -1, 0
	v_lshl_add_u64 v[154:155], v[128:129], 0, s[14:15]
	v_add_u32_e32 v168, 0, v19
	s_barrier
	s_branch .LBB0_134

; #define PG8_STAGE(bufoff, gbase, voff) do { _Pragma("unroll") for (int _i = 0; _i < 2; ++_i) \
;         __builtin_amdgcn_global_load_lds((const unsigned*)((const char*)(gbase) + (voff)[_i]), (PG8_LAS unsigned*)(lds + (bufoff) + ldsw + _i * 8192), 16, 0, 0); } while (0)
; #define PG8_WAIT_V(n) asm volatile("s_waitcnt vmcnt(" #n ")" ::: "memory")
; #define PG8_BAR __builtin_amdgcn_s_barrier()
; template <class Epi, class Sched, bool STAMP = false>
; __device__ __forceinline__ void gemm_phase(PG8_LAS unsigned char* lds, const Gemm g, const Sched& S, const Epi& E, unsigned long long* stamps) {
;     ...
;     f32x4 acc[2][2][4][2];
; #pragma unroll
;     for (int a = 0; a < 2; ++a)
; #pragma unroll
;         for (int b = 0; b < 2; ++b)
; #pragma unroll
;             for (int m = 0; m < 4; ++m)
; #pragma unroll
;                 for (int n = 0; n < 2; ++n) acc[a][b][m][n] = (f32x4){0.f, 0.f, 0.f, 0.f};
;     bf16x8 At[4][2], B0[2][2], B1[2][2];
;     const char* cA = (const char*)g.A + (size_t)cur.pm * tstep; const char* cB = (const char*)g.Bt + (size_t)cur.pn * tstep;
;     S.a_ready(cur);
;     PG8_STAGE(PG8_SB(0, 0), cB, voffB); PG8_STAGE(PG8_SA(0, 0), cA, voffA); PG8_STAGE(PG8_SB(0, 1), cB + hstep, voffB); PG8_STAGE(PG8_SA(0, 1), cA + hstep, voffA);
;     if (wr == 1) PG8_BAR;
;     PG8_WAIT_V(4); PG8_BAR;
;     PG8_STAGE(PG8_SB(1, 0), cB + kstep, voffB); PG8_STAGE(PG8_SA(1, 0), cA + kstep, voffA); PG8_STAGE(PG8_SB(1, 1), cB + hstep + kstep, voffB);
;     PG8_WAIT_V(6); PG8_BAR;
.LBB0_212:
	v_bfe_u32 v139, v0, 4, 2
	s_lshl_b32 s12, s12, 5
	v_and_b32_e32 v150, 15, v0
	v_lshlrev_b32_e32 v1, 4, v139
	v_lshlrev_b32_e32 v0, 2, v0
	s_and_b32 s56, s12, 0x60
	v_lshl_add_u64 v[2:3], s[0:1], 0, v[128:129]
	v_mov_b32_e32 v149, v129
	s_lshl_b32 s53, s13, 6
	v_lshl_or_b32 v1, v150, 6, v1
	s_lshl_b32 s13, s13, 13
	v_and_b32_e32 v0, 32, v0
	s_lshl_b32 s12, s56, 7
	v_lshl_add_u64 v[4:5], s[0:1], 0, v[148:149]
	v_bitop3_b32 v10, v1, s13, v0 bitop3:0xde
	v_bitop3_b32 v151, v1, s12, v0 bitop3:0xde
	s_add_i32 m0, s45, 0x18000
	v_lshl_add_u64 v[0:1], v[2:3], 0, s[18:19]
	v_lshl_add_u64 v[6:7], s[4:5], 0, v[128:129]
	s_nop 0
	global_load_lds_dwordx4 v[0:1], off
	v_lshl_add_u64 v[0:1], v[4:5], 0, s[18:19]
	s_add_i32 m0, s45, 0x1a000
	s_add_i32 s57, s45, 0x8000
	s_add_i32 s58, s45, 0xa000
	v_lshl_add_u64 v[8:9], s[4:5], 0, v[148:149]
	global_load_lds_dwordx4 v[0:1], off
	v_lshl_add_u64 v[0:1], v[6:7], 0, s[18:19]
	s_mov_b32 m0, s57
	s_add_u32 s12, s0, 0x40080
	global_load_lds_dwordx4 v[0:1], off
	v_lshl_add_u64 v[0:1], v[8:9], 0, s[18:19]
	s_mov_b32 m0, s58
	s_addc_u32 s13, s1, 0
	global_load_lds_dwordx4 v[0:1], off
	s_add_i32 m0, s45, 0x1c000
	v_lshl_add_u64 v[0:1], s[12:13], 0, v[128:129]
	global_load_lds_dwordx4 v[0:1], off
	v_lshl_add_u64 v[0:1], s[12:13], 0, v[148:149]
	s_add_i32 m0, s45, 0x1e000
	s_mov_b32 s14, 0
	global_load_lds_dwordx4 v[0:1], off
	s_waitcnt vmcnt(10)
	s_barrier
	s_waitcnt vmcnt(6)
	v_mov_b32_e32 v0, 0
	s_mov_b64 s[12:13], -1
	s_mov_b64 s[20:21], 0
	v_add_u32_e32 v152, 0, v10
	v_mov_b32_e32 v1, v0
	v_mov_b32_e32 v2, v0
	v_mov_b32_e32 v3, v0
	v_mov_b32_e32 v4, v0
	v_mov_b32_e32 v5, v0
	v_mov_b32_e32 v6, v0
	v_mov_b32_e32 v7, v0
	v_mov_b32_e32 v8, v0
	v_mov_b32_e32 v9, v0
	v_mov_b32_e32 v10, v0
	v_mov_b32_e32 v11, v0
	v_mov_b32_e32 v12, v0
	v_mov_b32_e32 v13, v0
	v_mov_b32_e32 v14, v0
	v_mov_b32_e32 v15, v0
	v_mov_b32_e32 v24, v0
	v_mov_b32_e32 v25, v0
	v_mov_b32_e32 v26, v0
	v_mov_b32_e32 v27, v0
	v_mov_b32_e32 v28, v0
	v_mov_b32_e32 v29, v0
	v_mov_b32_e32 v30, v0
	v_mov_b32_e32 v31, v0
	v_mov_b32_e32 v40, v0
	v_mov_b32_e32 v41, v0
	v_mov_b32_e32 v42, v0
	v_mov_b32_e32 v43, v0
	v_mov_b32_e32 v44, v0
	v_mov_b32_e32 v45, v0
	v_mov_b32_e32 v46, v0
	v_mov_b32_e32 v47, v0
	v_mov_b32_e32 v16, v0
	v_mov_b32_e32 v17, v0
	v_mov_b32_e32 v18, v0
	v_mov_b32_e32 v19, v0
	v_mov_b32_e32 v20, v0
	v_mov_b32_e32 v21, v0
	v_mov_b32_e32 v22, v0
	v_mov_b32_e32 v23, v0
	v_mov_b32_e32 v32, v0
	v_mov_b32_e32 v33, v0
	v_mov_b32_e32 v34, v0
	v_mov_b32_e32 v35, v0
	v_mov_b32_e32 v36, v0
	v_mov_b32_e32 v37, v0
	v_mov_b32_e32 v38, v0
	v_mov_b32_e32 v39, v0
	v_mov_b32_e32 v48, v0
	v_mov_b32_e32 v49, v0
	v_mov_b32_e32 v50, v0
	v_mov_b32_e32 v51, v0
	v_mov_b32_e32 v52, v0
	v_mov_b32_e32 v53, v0
	v_mov_b32_e32 v54, v0
	v_mov_b32_e32 v55, v0
	v_mov_b32_e32 v56, v0
	v_mov_b32_e32 v57, v0
	v_mov_b32_e32 v58, v0
	v_mov_b32_e32 v59, v0
	v_mov_b32_e32 v60, v0
	v_mov_b32_e32 v61, v0
	v_mov_b32_e32 v62, v0
	v_mov_b32_e32 v63, v0
	v_mov_b32_e32 v64, v0
	v_mov_b32_e32 v65, v0
	v_mov_b32_e32 v66, v0
	v_mov_b32_e32 v67, v0
	v_mov_b32_e32 v68, v0
	v_mov_b32_e32 v69, v0
	v_mov_b32_e32 v70, v0
	v_mov_b32_e32 v71, v0
	v_mov_b32_e32 v72, v0
	v_mov_b32_e32 v73, v0
	v_mov_b32_e32 v74, v0
	v_mov_b32_e32 v75, v0
	v_mov_b32_e32 v76, v0
	v_mov_b32_e32 v77, v0
	v_mov_b32_e32 v78, v0
	v_mov_b32_e32 v79, v0
	v_mov_b32_e32 v84, v0
	v_mov_b32_e32 v85, v0
	v_mov_b32_e32 v86, v0
	v_mov_b32_e32 v87, v0
	v_mov_b32_e32 v92, v0
	v_mov_b32_e32 v93, v0
	v_mov_b32_e32 v94, v0
	v_mov_b32_e32 v95, v0
	v_mov_b32_e32 v100, v0
	v_mov_b32_e32 v101, v0
	v_mov_b32_e32 v102, v0
	v_mov_b32_e32 v103, v0
	v_mov_b32_e32 v108, v0
	v_mov_b32_e32 v109, v0
	v_mov_b32_e32 v110, v0
	v_mov_b32_e32 v111, v0
	v_mov_b32_e32 v80, v0
	v_mov_b32_e32 v81, v0
	v_mov_b32_e32 v82, v0
	v_mov_b32_e32 v83, v0
	v_mov_b32_e32 v88, v0
	v_mov_b32_e32 v89, v0
	v_mov_b32_e32 v90, v0
	v_mov_b32_e32 v91, v0
	v_mov_b32_e32 v96, v0
	v_mov_b32_e32 v97, v0
	v_mov_b32_e32 v98, v0
	v_mov_b32_e32 v99, v0
	v_mov_b32_e32 v104, v0
	v_mov_b32_e32 v105, v0
	v_mov_b32_e32 v106, v0
	v_mov_b32_e32 v107, v0
	v_mov_b32_e32 v112, v0
	v_mov_b32_e32 v113, v0
	v_mov_b32_e32 v114, v0
	v_mov_b32_e32 v115, v0
	v_mov_b32_e32 v116, v0
	v_mov_b32_e32 v117, v0
	v_mov_b32_e32 v118, v0
	v_mov_b32_e32 v119, v0
	v_mov_b32_e32 v120, v0
	v_mov_b32_e32 v121, v0
	v_mov_b32_e32 v122, v0
	v_mov_b32_e32 v123, v0
	v_mov_b32_e32 v124, v0
	v_mov_b32_e32 v125, v0
	v_mov_b32_e32 v126, v0
	v_mov_b32_e32 v127, v0
	s_barrier

; #define PG8_STAGE(bufoff, gbase, voff) do { _Pragma("unroll") for (int _i = 0; _i < 2; ++_i) \
;         __builtin_amdgcn_global_load_lds((const unsigned*)((const char*)(gbase) + (voff)[_i]), (PG8_LAS unsigned*)(lds + (bufoff) + ldsw + _i * 8192), 16, 0, 0); } while (0)
; #define PG8_WAIT_V(n) asm volatile("s_waitcnt vmcnt(" #n ")" ::: "memory")
; #define PG8_BAR __builtin_amdgcn_s_barrier()
;     __device__ bool next(int i, pg8::Unit& u) const { if (i != 0 || !valid) return false; u.pm = pm; u.pn = pn; return true; }
; template <class Epi, class Sched, bool STAMP = false>
; __device__ __forceinline__ void gemm_phase(PG8_LAS unsigned char* lds, const Gemm g, const Sched& S, const Epi& E, unsigned long long* stamps) {
;     ...
;     for (int i = 0; i < 2; ++i) { int R, C; stage_rc(tid * 16 + i * 8192, R, C); const int Rb = Epi::PERM ? ((R & ~31) + perm32(R & 31)) : R;
;         voffA[i] = (unsigned)(R * LD + C) * 2u; voffB[i] = (unsigned)(Rb * LD + C) * 2u; }
;     const size_t kstep = (size_t)(BK * 2);
;     const size_t hstep = (size_t)HALF * LD * 2;
;     const size_t tstep = 2 * hstep;
;     const unsigned ldsw = (unsigned)wid * 1024u;
;     const int aoff = lds_byte(wr * 64 + fr, fq * 8), boff = lds_byte(wc * 32 + fr, fq * 8);
;     ...
;     Unit cur, nxt; int ui = 0;
;     if (!S.next(0, cur)) return;
;     f32x4 acc[2][2][4][2];
; #pragma unroll
;     for (int a = 0; a < 2; ++a)
; #pragma unroll
;         for (int b = 0; b < 2; ++b)
; #pragma unroll
;             for (int m = 0; m < 4; ++m)
; #pragma unroll
;                 for (int n = 0; n < 2; ++n) acc[a][b][m][n] = (f32x4){0.f, 0.f, 0.f, 0.f};
;     bf16x8 At[4][2], B0[2][2], B1[2][2];
;     const char* cA = (const char*)g.A + (size_t)cur.pm * tstep; const char* cB = (const char*)g.Bt + (size_t)cur.pn * tstep;
;     S.a_ready(cur);
;     PG8_STAGE(PG8_SB(0, 0), cB, voffB); PG8_STAGE(PG8_SA(0, 0), cA, voffA); PG8_STAGE(PG8_SB(0, 1), cB + hstep, voffB); PG8_STAGE(PG8_SA(0, 1), cA + hstep, voffA);
;     if (wr == 1) PG8_BAR;
;     PG8_WAIT_V(4); PG8_BAR;
;     PG8_STAGE(PG8_SB(1, 0), cB + kstep, voffB); PG8_STAGE(PG8_SA(1, 0), cA + kstep, voffA); PG8_STAGE(PG8_SB(1, 1), cB + hstep + kstep, voffB);
;     PG8_WAIT_V(6); PG8_BAR;
.LBB0_285:
	v_lshrrev_b32_e32 v16, 1, v6
	v_and_b32_e32 v16, 24, v16
	v_and_b32_e32 v7, 15, v6
	v_lshlrev_b32_e32 v17, 1, v16
	v_lshlrev_b32_e32 v6, 2, v6
	s_sext_i32_i8 s49, s4
	v_lshl_or_b32 v139, s5, 6, v7
	v_lshl_or_b32 v7, v7, 6, v17
	s_lshl_b32 s4, s5, 13
	v_and_b32_e32 v6, 32, v6
	v_bitop3_b32 v17, v7, s4, v6 bitop3:0xde
	s_lshl_b32 s4, s6, 5
	s_and_b32 s6, s4, 0x60
	v_lshl_add_u64 v[8:9], s[26:27], 0, v[128:129]
	v_mov_b32_e32 v153, v129
	s_lshl_b32 s4, s6, 7
	v_lshl_add_u64 v[10:11], s[26:27], 0, v[152:153]
	v_mov_b32_e32 v149, v129
	v_bitop3_b32 v158, v7, s4, v6 bitop3:0xde
	s_add_i32 m0, s3, 0x18000
	v_lshl_add_u64 v[6:7], v[8:9], 0, s[18:19]
	v_lshl_add_u64 v[12:13], s[24:25], 0, v[148:149]
	v_mov_b32_e32 v151, v129
	s_nop 0
	global_load_lds_dwordx4 v[6:7], off
	v_lshl_add_u64 v[6:7], v[10:11], 0, s[18:19]
	s_add_i32 m0, s3, 0x1a000
	s_add_i32 s46, s3, 0x8000
	s_add_i32 s47, s3, 0xa000
	v_lshl_add_u64 v[14:15], s[24:25], 0, v[150:151]
	global_load_lds_dwordx4 v[6:7], off
	v_lshl_add_u64 v[6:7], v[12:13], 0, s[18:19]
	s_mov_b32 m0, s46
	s_add_u32 s4, s26, 0x20080
	global_load_lds_dwordx4 v[6:7], off
	v_lshl_add_u64 v[6:7], v[14:15], 0, s[18:19]
	s_mov_b32 m0, s47
	s_addc_u32 s5, s27, 0
	global_load_lds_dwordx4 v[6:7], off
	s_add_i32 m0, s3, 0x1c000
	v_lshl_add_u64 v[6:7], s[4:5], 0, v[128:129]
	global_load_lds_dwordx4 v[6:7], off
	v_lshl_add_u64 v[6:7], s[4:5], 0, v[152:153]
	s_add_i32 m0, s3, 0x1e000
	v_or_b32_e32 v159, s6, v16
	global_load_lds_dwordx4 v[6:7], off
	v_lshlrev_b32_e32 v6, 13, v0
	v_and_b32_e32 v6, 0xffffc000, v6
	v_lshl_add_u32 v1, v1, 10, v6
	v_and_b32_e32 v0, 1, v0
	v_lshl_or_b32 v0, v0, 6, v1
	v_lshl_add_u32 v154, v2, 1, v0
	v_lshlrev_b32_e32 v0, 13, v3
	v_and_b32_e32 v0, 0xffffc000, v0
	s_waitcnt vmcnt(10)
	s_barrier
	s_waitcnt vmcnt(6)
	v_lshl_add_u32 v0, v4, 10, v0
	v_and_b32_e32 v1, 1, v3
	v_lshl_or_b32 v0, v1, 6, v0
	v_mov_b32_e32 v155, v129
	v_lshl_add_u32 v156, v5, 1, v0
	v_mov_b32_e32 v157, v129
	s_mov_b32 s48, 0
	v_add_u32_e32 v160, 0, v17
	s_barrier

; #define PG8_STAGE(bufoff, gbase, voff) do { _Pragma("unroll") for (int _i = 0; _i < 2; ++_i) \
;         __builtin_amdgcn_global_load_lds((const unsigned*)((const char*)(gbase) + (voff)[_i]), (PG8_LAS unsigned*)(lds + (bufoff) + ldsw + _i * 8192), 16, 0, 0); } while (0)
; #define PG8_WAIT_V(n) asm volatile("s_waitcnt vmcnt(" #n ")" ::: "memory")
; #define PG8_BAR __builtin_amdgcn_s_barrier()
;     __device__ bool next(int i, pg8::Unit& u) const { if (i != 0 || !valid) return false; u.pm = pm; u.pn = pn; return true; }
; template <class Epi, class Sched, bool STAMP = false>
; __device__ __forceinline__ void gemm_phase(PG8_LAS unsigned char* lds, const Gemm g, const Sched& S, const Epi& E, unsigned long long* stamps) {
;     ...
;     for (int i = 0; i < 2; ++i) { int R, C; stage_rc(tid * 16 + i * 8192, R, C); const int Rb = Epi::PERM ? ((R & ~31) + perm32(R & 31)) : R;
;         voffA[i] = (unsigned)(R * LD + C) * 2u; voffB[i] = (unsigned)(Rb * LD + C) * 2u; }
;     const size_t kstep = (size_t)(BK * 2);
;     const size_t hstep = (size_t)HALF * LD * 2;
;     const size_t tstep = 2 * hstep;
;     const unsigned ldsw = (unsigned)wid * 1024u;
;     const int aoff = lds_byte(wr * 64 + fr, fq * 8), boff = lds_byte(wc * 32 + fr, fq * 8);
;     ...
;     Unit cur, nxt; int ui = 0;
;     if (!S.next(0, cur)) return;
;     f32x4 acc[2][2][4][2];
; #pragma unroll
;     for (int a = 0; a < 2; ++a)
; #pragma unroll
;         for (int b = 0; b < 2; ++b)
; #pragma unroll
;             for (int m = 0; m < 4; ++m)
; #pragma unroll
;                 for (int n = 0; n < 2; ++n) acc[a][b][m][n] = (f32x4){0.f, 0.f, 0.f, 0.f};
;     bf16x8 At[4][2], B0[2][2], B1[2][2];
;     const char* cA = (const char*)g.A + (size_t)cur.pm * tstep; const char* cB = (const char*)g.Bt + (size_t)cur.pn * tstep;
;     S.a_ready(cur);
;     PG8_STAGE(PG8_SB(0, 0), cB, voffB); PG8_STAGE(PG8_SA(0, 0), cA, voffA); PG8_STAGE(PG8_SB(0, 1), cB + hstep, voffB); PG8_STAGE(PG8_SA(0, 1), cA + hstep, voffA);
;     if (wr == 1) PG8_BAR;
;     PG8_WAIT_V(4); PG8_BAR;
;     PG8_STAGE(PG8_SB(1, 0), cB + kstep, voffB); PG8_STAGE(PG8_SA(1, 0), cA + kstep, voffA); PG8_STAGE(PG8_SB(1, 1), cB + hstep + kstep, voffB);
;     PG8_WAIT_V(6); PG8_BAR;
.LBB0_305:
	v_lshrrev_b32_e32 v16, 1, v6
	v_and_b32_e32 v16, 24, v16
	v_and_b32_e32 v7, 15, v6
	v_lshlrev_b32_e32 v17, 1, v16
	v_lshlrev_b32_e32 v6, 2, v6
	s_sext_i32_i8 s46, s6
	v_lshl_or_b32 v139, s7, 6, v7
	v_lshl_or_b32 v7, v7, 6, v17
	s_lshl_b32 s6, s7, 13
	v_and_b32_e32 v6, 32, v6
	v_bitop3_b32 v17, v7, s6, v6 bitop3:0xde
	s_lshl_b32 s6, s14, 5
	s_and_b32 s14, s6, 0x60
	v_lshl_add_u64 v[8:9], s[12:13], 0, v[128:129]
	v_mov_b32_e32 v153, v129
	s_lshl_b32 s6, s14, 7
	v_lshl_add_u64 v[10:11], s[12:13], 0, v[152:153]
	v_mov_b32_e32 v149, v129
	v_bitop3_b32 v167, v7, s6, v6 bitop3:0xde
	s_add_i32 m0, s3, 0x18000
	v_lshl_add_u64 v[6:7], v[8:9], 0, s[18:19]
	v_lshl_add_u64 v[12:13], s[4:5], 0, v[148:149]
	v_mov_b32_e32 v151, v129
	s_nop 0
	global_load_lds_dwordx4 v[6:7], off
	v_lshl_add_u64 v[6:7], v[10:11], 0, s[18:19]
	s_add_i32 m0, s3, 0x1a000
	s_add_i32 s60, s3, 0x8000
	s_add_i32 s61, s3, 0xa000
	v_lshl_add_u64 v[14:15], s[4:5], 0, v[150:151]
	global_load_lds_dwordx4 v[6:7], off
	v_lshl_add_u64 v[6:7], v[12:13], 0, s[18:19]
	s_mov_b32 m0, s60
	s_add_u32 s6, s12, 0x40080
	global_load_lds_dwordx4 v[6:7], off
	v_lshl_add_u64 v[6:7], v[14:15], 0, s[18:19]
	s_mov_b32 m0, s61
	s_addc_u32 s7, s13, 0
	global_load_lds_dwordx4 v[6:7], off
	s_add_i32 m0, s3, 0x1c000
	v_lshl_add_u64 v[6:7], s[6:7], 0, v[128:129]
	global_load_lds_dwordx4 v[6:7], off
	v_lshl_add_u64 v[6:7], s[6:7], 0, v[152:153]
	s_add_i32 m0, s3, 0x1e000
	v_or_b32_e32 v168, s14, v16
	global_load_lds_dwordx4 v[6:7], off
	v_lshlrev_b32_e32 v6, 14, v0
	v_and_b32_e32 v6, 0xffff8000, v6
	v_lshl_add_u32 v1, v1, 11, v6
	v_and_b32_e32 v0, 1, v0
	v_lshl_or_b32 v0, v0, 6, v1
	v_lshl_add_u32 v154, v2, 1, v0
	v_lshlrev_b32_e32 v0, 14, v3
	v_and_b32_e32 v0, 0xffff8000, v0
	s_waitcnt vmcnt(10)
	s_barrier
	s_waitcnt vmcnt(6)
	v_lshl_add_u32 v0, v4, 11, v0
	v_and_b32_e32 v1, 1, v3
	v_lshl_or_b32 v0, v1, 6, v0
	v_mov_b32_e32 v155, v129
	v_lshl_add_u32 v156, v5, 1, v0
	v_mov_b32_e32 v157, v129
	s_mov_b32 s64, 0
	v_add_u32_e32 v169, 0, v17
	s_barrier

; #define PG8_STAGE(bufoff, gbase, voff) do { _Pragma("unroll") for (int _i = 0; _i < 2; ++_i) \
;         __builtin_amdgcn_global_load_lds((const unsigned*)((const char*)(gbase) + (voff)[_i]), (PG8_LAS unsigned*)(lds + (bufoff) + ldsw + _i * 8192), 16, 0, 0); } while (0)
; #define PG8_WAIT_V(n) asm volatile("s_waitcnt vmcnt(" #n ")" ::: "memory")
; #define PG8_BAR __builtin_amdgcn_s_barrier()
;     __device__ bool next(int i, pg8::Unit& u) const { if (i != 0 || !valid) return false; u.pm = pm; u.pn = pn; return true; }
; template <class Epi, class Sched, bool STAMP = false>
; __device__ __forceinline__ void gemm_phase(PG8_LAS unsigned char* lds, const Gemm g, const Sched& S, const Epi& E, unsigned long long* stamps) {
;     ...
;     for (int i = 0; i < 2; ++i) { int R, C; stage_rc(tid * 16 + i * 8192, R, C); const int Rb = Epi::PERM ? ((R & ~31) + perm32(R & 31)) : R;
;         voffA[i] = (unsigned)(R * LD + C) * 2u; voffB[i] = (unsigned)(Rb * LD + C) * 2u; }
;     const size_t kstep = (size_t)(BK * 2);
;     const size_t hstep = (size_t)HALF * LD * 2;
;     const size_t tstep = 2 * hstep;
;     const unsigned ldsw = (unsigned)wid * 1024u;
;     const int aoff = lds_byte(wr * 64 + fr, fq * 8), boff = lds_byte(wc * 32 + fr, fq * 8);
;     ...
;     Unit cur, nxt; int ui = 0;
;     if (!S.next(0, cur)) return;
;     f32x4 acc[2][2][4][2];
; #pragma unroll
;     for (int a = 0; a < 2; ++a)
; #pragma unroll
;         for (int b = 0; b < 2; ++b)
; #pragma unroll
;             for (int m = 0; m < 4; ++m)
; #pragma unroll
;                 for (int n = 0; n < 2; ++n) acc[a][b][m][n] = (f32x4){0.f, 0.f, 0.f, 0.f};
;     bf16x8 At[4][2], B0[2][2], B1[2][2];
;     const char* cA = (const char*)g.A + (size_t)cur.pm * tstep; const char* cB = (const char*)g.Bt + (size_t)cur.pn * tstep;
;     S.a_ready(cur);
;     PG8_STAGE(PG8_SB(0, 0), cB, voffB); PG8_STAGE(PG8_SA(0, 0), cA, voffA); PG8_STAGE(PG8_SB(0, 1), cB + hstep, voffB); PG8_STAGE(PG8_SA(0, 1), cA + hstep, voffA);
;     if (wr == 1) PG8_BAR;
;     PG8_WAIT_V(4); PG8_BAR;
;     PG8_STAGE(PG8_SB(1, 0), cB + kstep, voffB); PG8_STAGE(PG8_SA(1, 0), cA + kstep, voffA); PG8_STAGE(PG8_SB(1, 1), cB + hstep + kstep, voffB);
;     PG8_WAIT_V(6); PG8_BAR;
.LBB0_325:
	v_lshrrev_b32_e32 v16, 1, v6
	v_and_b32_e32 v16, 24, v16
	v_and_b32_e32 v7, 15, v6
	v_lshlrev_b32_e32 v17, 1, v16
	v_lshlrev_b32_e32 v6, 2, v6
	s_sext_i32_i8 s76, s4
	v_lshl_or_b32 v139, s5, 6, v7
	v_lshl_or_b32 v7, v7, 6, v17
	s_lshl_b32 s4, s5, 13
	v_and_b32_e32 v6, 32, v6
	v_bitop3_b32 v17, v7, s4, v6 bitop3:0xde
	s_lshl_b32 s4, s12, 5
	s_and_b32 s12, s4, 0x60
	v_lshl_add_u64 v[8:9], s[56:57], 0, v[128:129]
	v_mov_b32_e32 v153, v129
	s_lshl_b32 s4, s12, 7
	v_lshl_add_u64 v[10:11], s[56:57], 0, v[152:153]
	v_mov_b32_e32 v149, v129
	v_bitop3_b32 v158, v7, s4, v6 bitop3:0xde
	s_add_i32 m0, s3, 0x18000
	v_lshl_add_u64 v[6:7], v[8:9], 0, s[18:19]
	v_lshl_add_u64 v[12:13], s[36:37], 0, v[148:149]
	v_mov_b32_e32 v151, v129
	s_nop 0
	global_load_lds_dwordx4 v[6:7], off
	v_lshl_add_u64 v[6:7], v[10:11], 0, s[18:19]
	s_add_i32 m0, s3, 0x1a000
	s_add_i32 s63, s3, 0x8000
	s_add_i32 s64, s3, 0xa000
	v_lshl_add_u64 v[14:15], s[36:37], 0, v[150:151]
	global_load_lds_dwordx4 v[6:7], off
	v_lshl_add_u64 v[6:7], v[12:13], 0, s[18:19]
	s_mov_b32 m0, s63
	s_add_u32 s4, s56, 0x20080
	global_load_lds_dwordx4 v[6:7], off
	v_lshl_add_u64 v[6:7], v[14:15], 0, s[18:19]
	s_mov_b32 m0, s64
	s_addc_u32 s5, s57, 0
	global_load_lds_dwordx4 v[6:7], off
	s_add_i32 m0, s3, 0x1c000
	v_lshl_add_u64 v[6:7], s[4:5], 0, v[128:129]
	global_load_lds_dwordx4 v[6:7], off
	v_lshl_add_u64 v[6:7], s[4:5], 0, v[152:153]
	s_add_i32 m0, s3, 0x1e000
	v_or_b32_e32 v159, s12, v16
	global_load_lds_dwordx4 v[6:7], off
	v_lshlrev_b32_e32 v6, 13, v0
	v_and_b32_e32 v6, 0xffffc000, v6
	v_lshl_add_u32 v1, v1, 10, v6
	v_and_b32_e32 v0, 1, v0
	v_lshl_or_b32 v0, v0, 6, v1
	v_lshl_add_u32 v154, v2, 1, v0
	v_lshlrev_b32_e32 v0, 13, v3
	v_and_b32_e32 v0, 0xffffc000, v0
	s_waitcnt vmcnt(10)
	s_barrier
	s_waitcnt vmcnt(6)
	v_lshl_add_u32 v0, v4, 10, v0
	v_and_b32_e32 v1, 1, v3
	v_lshl_or_b32 v0, v1, 6, v0
	v_mov_b32_e32 v155, v129
	v_lshl_add_u32 v156, v5, 1, v0
	v_mov_b32_e32 v157, v129
	s_mov_b32 s65, 0
	v_add_u32_e32 v160, 0, v17
	s_barrier

; #define PG8_STAGE(bufoff, gbase, voff) do { _Pragma("unroll") for (int _i = 0; _i < 2; ++_i) \
;         __builtin_amdgcn_global_load_lds((const unsigned*)((const char*)(gbase) + (voff)[_i]), (PG8_LAS unsigned*)(lds + (bufoff) + ldsw + _i * 8192), 16, 0, 0); } while (0)
; #define PG8_WAIT_V(n) asm volatile("s_waitcnt vmcnt(" #n ")" ::: "memory")
; #define PG8_BAR __builtin_amdgcn_s_barrier()
;     __device__ bool next(int i, pg8::Unit& u) const { if (i != 0 || !valid) return false; u.pm = pm; u.pn = pn; return true; }
; template <class Epi, class Sched, bool STAMP = false>
; __device__ __forceinline__ void gemm_phase(PG8_LAS unsigned char* lds, const Gemm g, const Sched& S, const Epi& E, unsigned long long* stamps) {
;     ...
;     for (int i = 0; i < 2; ++i) { int R, C; stage_rc(tid * 16 + i * 8192, R, C); const int Rb = Epi::PERM ? ((R & ~31) + perm32(R & 31)) : R;
;         voffA[i] = (unsigned)(R * LD + C) * 2u; voffB[i] = (unsigned)(Rb * LD + C) * 2u; }
;     const size_t kstep = (size_t)(BK * 2);
;     const size_t hstep = (size_t)HALF * LD * 2;
;     const size_t tstep = 2 * hstep;
;     const unsigned ldsw = (unsigned)wid * 1024u;
;     const int aoff = lds_byte(wr * 64 + fr, fq * 8), boff = lds_byte(wc * 32 + fr, fq * 8);
;     ...
;     Unit cur, nxt; int ui = 0;
;     if (!S.next(0, cur)) return;
;     f32x4 acc[2][2][4][2];
; #pragma unroll
;     for (int a = 0; a < 2; ++a)
; #pragma unroll
;         for (int b = 0; b < 2; ++b)
; #pragma unroll
;             for (int m = 0; m < 4; ++m)
; #pragma unroll
;                 for (int n = 0; n < 2; ++n) acc[a][b][m][n] = (f32x4){0.f, 0.f, 0.f, 0.f};
;     bf16x8 At[4][2], B0[2][2], B1[2][2];
;     const char* cA = (const char*)g.A + (size_t)cur.pm * tstep; const char* cB = (const char*)g.Bt + (size_t)cur.pn * tstep;
;     S.a_ready(cur);
;     PG8_STAGE(PG8_SB(0, 0), cB, voffB); PG8_STAGE(PG8_SA(0, 0), cA, voffA); PG8_STAGE(PG8_SB(0, 1), cB + hstep, voffB); PG8_STAGE(PG8_SA(0, 1), cA + hstep, voffA);
;     if (wr == 1) PG8_BAR;
;     PG8_WAIT_V(4); PG8_BAR;
;     PG8_STAGE(PG8_SB(1, 0), cB + kstep, voffB); PG8_STAGE(PG8_SA(1, 0), cA + kstep, voffA); PG8_STAGE(PG8_SB(1, 1), cB + hstep + kstep, voffB);
;     PG8_WAIT_V(6); PG8_BAR;
.LBB0_345:
	v_lshrrev_b32_e32 v16, 1, v6
	v_and_b32_e32 v16, 24, v16
	v_and_b32_e32 v7, 15, v6
	v_lshlrev_b32_e32 v17, 1, v16
	v_lshlrev_b32_e32 v6, 2, v6
	s_sext_i32_i8 s3, s4
	v_lshl_or_b32 v139, s5, 6, v7
	v_lshl_or_b32 v7, v7, 6, v17
	s_lshl_b32 s4, s5, 13
	v_and_b32_e32 v6, 32, v6
	v_bitop3_b32 v17, v7, s4, v6 bitop3:0xde
	s_lshl_b32 s4, s12, 5
	s_and_b32 s12, s4, 0x60
	v_lshl_add_u64 v[8:9], s[58:59], 0, v[128:129]
	v_mov_b32_e32 v153, v129
	s_lshl_b32 s4, s12, 7
	v_lshl_add_u64 v[10:11], s[58:59], 0, v[152:153]
	v_mov_b32_e32 v149, v129
	v_bitop3_b32 v167, v7, s4, v6 bitop3:0xde
	s_add_i32 m0, s89, 0x18000
	v_lshl_add_u64 v[6:7], v[8:9], 0, s[18:19]
	v_lshl_add_u64 v[12:13], s[56:57], 0, v[148:149]
	v_mov_b32_e32 v151, v129
	s_nop 0
	global_load_lds_dwordx4 v[6:7], off
	v_lshl_add_u64 v[6:7], v[10:11], 0, s[18:19]
	s_add_i32 m0, s89, 0x1a000
	s_add_i32 s62, s89, 0x8000
	s_add_i32 s63, s89, 0xa000
	v_lshl_add_u64 v[14:15], s[56:57], 0, v[150:151]
	global_load_lds_dwordx4 v[6:7], off
	v_lshl_add_u64 v[6:7], v[12:13], 0, s[18:19]
	s_mov_b32 m0, s62
	s_add_u32 s4, s58, 0x40080
	global_load_lds_dwordx4 v[6:7], off
	v_lshl_add_u64 v[6:7], v[14:15], 0, s[18:19]
	s_mov_b32 m0, s63
	s_addc_u32 s5, s59, 0
	global_load_lds_dwordx4 v[6:7], off
	s_add_i32 m0, s89, 0x1c000
	v_lshl_add_u64 v[6:7], s[4:5], 0, v[128:129]
	global_load_lds_dwordx4 v[6:7], off
	v_lshl_add_u64 v[6:7], s[4:5], 0, v[152:153]
	s_add_i32 m0, s89, 0x1e000
	v_or_b32_e32 v170, s12, v16
	global_load_lds_dwordx4 v[6:7], off
	v_lshlrev_b32_e32 v6, 14, v0
	v_and_b32_e32 v6, 0xffff8000, v6
	v_lshl_add_u32 v1, v1, 11, v6
	v_and_b32_e32 v0, 1, v0
	v_lshl_or_b32 v0, v0, 6, v1
	v_lshl_add_u32 v154, v2, 1, v0
	v_lshlrev_b32_e32 v0, 14, v3
	v_and_b32_e32 v0, 0xffff8000, v0
	s_waitcnt vmcnt(10)
	s_barrier
	s_waitcnt vmcnt(6)
	v_lshl_add_u32 v0, v4, 11, v0
	v_and_b32_e32 v1, 1, v3
	v_lshl_or_b32 v0, v1, 6, v0
	v_mov_b32_e32 v155, v129
	v_lshl_add_u32 v156, v5, 1, v0
	v_mov_b32_e32 v157, v129
	s_mov_b32 s46, 0
	v_add_u32_e32 v171, 0, v17
	s_barrier

; #define PG8_STAGE(bufoff, gbase, voff) do { _Pragma("unroll") for (int _i = 0; _i < 2; ++_i) \
;         __builtin_amdgcn_global_load_lds((const unsigned*)((const char*)(gbase) + (voff)[_i]), (PG8_LAS unsigned*)(lds + (bufoff) + ldsw + _i * 8192), 16, 0, 0); } while (0)
; #define PG8_WAIT_V(n) asm volatile("s_waitcnt vmcnt(" #n ")" ::: "memory")
; #define PG8_BAR __builtin_amdgcn_s_barrier()
; template <class Epi, class Sched, bool STAMP = false>
; __device__ __forceinline__ void gemm_phase(PG8_LAS unsigned char* lds, const Gemm g, const Sched& S, const Epi& E, unsigned long long* stamps) {
;     ...
;     f32x4 acc[2][2][4][2];
; #pragma unroll
;     for (int a = 0; a < 2; ++a)
; #pragma unroll
;         for (int b = 0; b < 2; ++b)
; #pragma unroll
;             for (int m = 0; m < 4; ++m)
; #pragma unroll
;                 for (int n = 0; n < 2; ++n) acc[a][b][m][n] = (f32x4){0.f, 0.f, 0.f, 0.f};
;     bf16x8 At[4][2], B0[2][2], B1[2][2];
;     const char* cA = (const char*)g.A + (size_t)cur.pm * tstep; const char* cB = (const char*)g.Bt + (size_t)cur.pn * tstep;
;     S.a_ready(cur);
;     PG8_STAGE(PG8_SB(0, 0), cB, voffB); PG8_STAGE(PG8_SA(0, 0), cA, voffA); PG8_STAGE(PG8_SB(0, 1), cB + hstep, voffB); PG8_STAGE(PG8_SA(0, 1), cA + hstep, voffA);
;     if (wr == 1) PG8_BAR;
;     PG8_WAIT_V(4); PG8_BAR;
;     PG8_STAGE(PG8_SB(1, 0), cB + kstep, voffB); PG8_STAGE(PG8_SA(1, 0), cA + kstep, voffA); PG8_STAGE(PG8_SB(1, 1), cB + hstep + kstep, voffB);
;     PG8_WAIT_V(6); PG8_BAR;
.LBB0_373:
	v_bfe_u32 v139, v0, 4, 2
	s_lshl_b32 s14, s14, 5
	v_and_b32_e32 v150, 15, v0
	v_lshlrev_b32_e32 v1, 4, v139
	v_lshlrev_b32_e32 v0, 2, v0
	s_and_b32 s53, s14, 0x60
	v_lshl_add_u64 v[2:3], s[4:5], 0, v[128:129]
	v_mov_b32_e32 v149, v129
	s_lshl_b32 s49, s15, 6
	v_lshl_or_b32 v1, v150, 6, v1
	s_lshl_b32 s15, s15, 13
	v_and_b32_e32 v0, 32, v0
	s_lshl_b32 s14, s53, 7
	v_lshl_add_u64 v[4:5], s[4:5], 0, v[148:149]
	v_bitop3_b32 v14, v1, s15, v0 bitop3:0xde
	v_bitop3_b32 v151, v1, s14, v0 bitop3:0xde
	s_add_i32 m0, s42, 0x18000
	v_lshl_add_u64 v[0:1], v[2:3], 0, s[18:19]
	v_lshl_add_u64 v[6:7], s[6:7], 0, v[128:129]
	s_nop 0
	global_load_lds_dwordx4 v[0:1], off
	v_lshl_add_u64 v[0:1], v[4:5], 0, s[18:19]
	s_add_i32 m0, s42, 0x1a000
	s_add_i32 s56, s42, 0x8000
	v_lshl_add_u64 v[8:9], s[6:7], 0, v[148:149]
	global_load_lds_dwordx4 v[0:1], off
	v_lshl_add_u64 v[0:1], v[6:7], 0, s[18:19]
	s_mov_b32 m0, s56
	s_add_i32 s57, s42, 0xa000
	v_lshl_add_u64 v[10:11], s[20:21], 0, v[128:129]
	global_load_lds_dwordx4 v[0:1], off
	v_lshl_add_u64 v[0:1], v[8:9], 0, s[18:19]
	s_mov_b32 m0, s57
	v_lshl_add_u64 v[12:13], s[20:21], 0, v[148:149]
	global_load_lds_dwordx4 v[0:1], off
	s_add_i32 m0, s42, 0x1c000
	v_lshl_add_u64 v[0:1], v[10:11], 0, s[18:19]
	global_load_lds_dwordx4 v[0:1], off
	v_lshl_add_u64 v[0:1], v[12:13], 0, s[18:19]
	s_add_i32 m0, s42, 0x1e000
	s_mov_b32 s14, 0
	global_load_lds_dwordx4 v[0:1], off
	s_waitcnt vmcnt(10)
	s_barrier
	s_waitcnt vmcnt(6)
	v_mov_b32_e32 v0, 0
	s_mov_b64 s[20:21], -1
	s_mov_b64 s[22:23], 0
	v_add_u32_e32 v152, 0, v14
	v_mov_b32_e32 v1, v0
	v_mov_b32_e32 v2, v0
	v_mov_b32_e32 v3, v0
	v_mov_b32_e32 v4, v0
	v_mov_b32_e32 v5, v0
	v_mov_b32_e32 v6, v0
	v_mov_b32_e32 v7, v0
	v_mov_b32_e32 v8, v0
	v_mov_b32_e32 v9, v0
	v_mov_b32_e32 v10, v0
	v_mov_b32_e32 v11, v0
	v_mov_b32_e32 v12, v0
	v_mov_b32_e32 v13, v0
	v_mov_b32_e32 v14, v0
	v_mov_b32_e32 v15, v0
	v_mov_b32_e32 v24, v0
	v_mov_b32_e32 v25, v0
	v_mov_b32_e32 v26, v0
	v_mov_b32_e32 v27, v0
	v_mov_b32_e32 v28, v0
	v_mov_b32_e32 v29, v0
	v_mov_b32_e32 v30, v0
	v_mov_b32_e32 v31, v0
	v_mov_b32_e32 v40, v0
	v_mov_b32_e32 v41, v0
	v_mov_b32_e32 v42, v0
	v_mov_b32_e32 v43, v0
	v_mov_b32_e32 v44, v0
	v_mov_b32_e32 v45, v0
	v_mov_b32_e32 v46, v0
	v_mov_b32_e32 v47, v0
	v_mov_b32_e32 v16, v0
	v_mov_b32_e32 v17, v0
	v_mov_b32_e32 v18, v0
	v_mov_b32_e32 v19, v0
	v_mov_b32_e32 v20, v0
	v_mov_b32_e32 v21, v0
	v_mov_b32_e32 v22, v0
	v_mov_b32_e32 v23, v0
	v_mov_b32_e32 v32, v0
	v_mov_b32_e32 v33, v0
	v_mov_b32_e32 v34, v0
	v_mov_b32_e32 v35, v0
	v_mov_b32_e32 v36, v0
	v_mov_b32_e32 v37, v0
	v_mov_b32_e32 v38, v0
	v_mov_b32_e32 v39, v0
	v_mov_b32_e32 v48, v0
	v_mov_b32_e32 v49, v0
	v_mov_b32_e32 v50, v0
	v_mov_b32_e32 v51, v0
	v_mov_b32_e32 v52, v0
	v_mov_b32_e32 v53, v0
	v_mov_b32_e32 v54, v0
	v_mov_b32_e32 v55, v0
	v_mov_b32_e32 v56, v0
	v_mov_b32_e32 v57, v0
	v_mov_b32_e32 v58, v0
	v_mov_b32_e32 v59, v0
	v_mov_b32_e32 v60, v0
	v_mov_b32_e32 v61, v0
	v_mov_b32_e32 v62, v0
	v_mov_b32_e32 v63, v0
	v_mov_b32_e32 v64, v0
	v_mov_b32_e32 v65, v0
	v_mov_b32_e32 v66, v0
	v_mov_b32_e32 v67, v0
	v_mov_b32_e32 v68, v0
	v_mov_b32_e32 v69, v0
	v_mov_b32_e32 v70, v0
	v_mov_b32_e32 v71, v0
	v_mov_b32_e32 v72, v0
	v_mov_b32_e32 v73, v0
	v_mov_b32_e32 v74, v0
	v_mov_b32_e32 v75, v0
	v_mov_b32_e32 v76, v0
	v_mov_b32_e32 v77, v0
	v_mov_b32_e32 v78, v0
	v_mov_b32_e32 v79, v0
	v_mov_b32_e32 v84, v0
	v_mov_b32_e32 v85, v0
	v_mov_b32_e32 v86, v0
	v_mov_b32_e32 v87, v0
	v_mov_b32_e32 v92, v0
	v_mov_b32_e32 v93, v0
	v_mov_b32_e32 v94, v0
	v_mov_b32_e32 v95, v0
	v_mov_b32_e32 v100, v0
	v_mov_b32_e32 v101, v0
	v_mov_b32_e32 v102, v0
	v_mov_b32_e32 v103, v0
	v_mov_b32_e32 v108, v0
	v_mov_b32_e32 v109, v0
	v_mov_b32_e32 v110, v0
	v_mov_b32_e32 v111, v0
	v_mov_b32_e32 v80, v0
	v_mov_b32_e32 v81, v0
	v_mov_b32_e32 v82, v0
	v_mov_b32_e32 v83, v0
	v_mov_b32_e32 v88, v0
	v_mov_b32_e32 v89, v0
	v_mov_b32_e32 v90, v0
	v_mov_b32_e32 v91, v0
	v_mov_b32_e32 v96, v0
	v_mov_b32_e32 v97, v0
	v_mov_b32_e32 v98, v0
	v_mov_b32_e32 v99, v0
	v_mov_b32_e32 v104, v0
	v_mov_b32_e32 v105, v0
	v_mov_b32_e32 v106, v0
	v_mov_b32_e32 v107, v0
	v_mov_b32_e32 v112, v0
	v_mov_b32_e32 v113, v0
	v_mov_b32_e32 v114, v0
	v_mov_b32_e32 v115, v0
	v_mov_b32_e32 v116, v0
	v_mov_b32_e32 v117, v0
	v_mov_b32_e32 v118, v0
	v_mov_b32_e32 v119, v0
	v_mov_b32_e32 v120, v0
	v_mov_b32_e32 v121, v0
	v_mov_b32_e32 v122, v0
	v_mov_b32_e32 v123, v0
	v_mov_b32_e32 v124, v0
	v_mov_b32_e32 v125, v0
	v_mov_b32_e32 v126, v0
	v_mov_b32_e32 v127, v0
	s_barrier

; #define PG8_STAGE(bufoff, gbase, voff) do { _Pragma("unroll") for (int _i = 0; _i < 2; ++_i) \
;         __builtin_amdgcn_global_load_lds((const unsigned*)((const char*)(gbase) + (voff)[_i]), (PG8_LAS unsigned*)(lds + (bufoff) + ldsw + _i * 8192), 16, 0, 0); } while (0)
; #define PG8_WAIT_V(n) asm volatile("s_waitcnt vmcnt(" #n ")" ::: "memory")
; #define PG8_BAR __builtin_amdgcn_s_barrier()
;     __device__ bool next(int i, pg8::Unit& u) const { if (i != 0 || !valid) return false; u.pm = pm; u.pn = pn; return true; }
; template <class Epi, class Sched, bool STAMP = false>
; __device__ __forceinline__ void gemm_phase(PG8_LAS unsigned char* lds, const Gemm g, const Sched& S, const Epi& E, unsigned long long* stamps) {
;     ...
;     for (int i = 0; i < 2; ++i) { int R, C; stage_rc(tid * 16 + i * 8192, R, C); const int Rb = Epi::PERM ? ((R & ~31) + perm32(R & 31)) : R;
;         voffA[i] = (unsigned)(R * LD + C) * 2u; voffB[i] = (unsigned)(Rb * LD + C) * 2u; }
;     const size_t kstep = (size_t)(BK * 2);
;     const size_t hstep = (size_t)HALF * LD * 2;
;     const size_t tstep = 2 * hstep;
;     const unsigned ldsw = (unsigned)wid * 1024u;
;     const int aoff = lds_byte(wr * 64 + fr, fq * 8), boff = lds_byte(wc * 32 + fr, fq * 8);
;     ...
;     Unit cur, nxt; int ui = 0;
;     if (!S.next(0, cur)) return;
;     f32x4 acc[2][2][4][2];
; #pragma unroll
;     for (int a = 0; a < 2; ++a)
; #pragma unroll
;         for (int b = 0; b < 2; ++b)
; #pragma unroll
;             for (int m = 0; m < 4; ++m)
; #pragma unroll
;                 for (int n = 0; n < 2; ++n) acc[a][b][m][n] = (f32x4){0.f, 0.f, 0.f, 0.f};
;     bf16x8 At[4][2], B0[2][2], B1[2][2];
;     const char* cA = (const char*)g.A + (size_t)cur.pm * tstep; const char* cB = (const char*)g.Bt + (size_t)cur.pn * tstep;
;     S.a_ready(cur);
;     PG8_STAGE(PG8_SB(0, 0), cB, voffB); PG8_STAGE(PG8_SA(0, 0), cA, voffA); PG8_STAGE(PG8_SB(0, 1), cB + hstep, voffB); PG8_STAGE(PG8_SA(0, 1), cA + hstep, voffA);
;     if (wr == 1) PG8_BAR;
;     PG8_WAIT_V(4); PG8_BAR;
;     PG8_STAGE(PG8_SB(1, 0), cB + kstep, voffB); PG8_STAGE(PG8_SA(1, 0), cA + kstep, voffA); PG8_STAGE(PG8_SB(1, 1), cB + hstep + kstep, voffB);
;     PG8_WAIT_V(6); PG8_BAR;
.LBB0_491:
	s_sext_i32_i8 s56, s0
	s_and_b64 s[0:1], s[34:35], exec
	s_cselect_b32 s0, 0x22000, 0
	s_add_u32 s0, s2, s0
	s_addc_u32 s1, s3, 0
	s_add_u32 s0, s0, 0x2060000
	s_addc_u32 s1, s1, 0
	s_add_u32 s2, s2, 0x5500000
	v_lshrrev_b32_e32 v16, 1, v14
	s_addc_u32 s3, s3, 0
	v_and_b32_e32 v16, 24, v16
	s_lshl_b32 s4, s4, 5
	v_and_b32_e32 v15, 15, v14
	v_lshlrev_b32_e32 v17, 1, v16
	v_lshlrev_b32_e32 v14, 2, v14
	s_and_b32 s6, s4, 0x60
	s_add_i32 m0, s23, 0x18000
	v_lshl_add_u64 v[6:7], v[6:7], 0, s[18:19]
	v_lshl_or_b32 v139, s5, 6, v15
	v_lshl_or_b32 v15, v15, 6, v17
	s_lshl_b32 s5, s5, 13
	v_and_b32_e32 v14, 32, v14
	s_lshl_b32 s4, s6, 7
	s_nop 0
	global_load_lds_dwordx4 v[6:7], off
	v_lshl_add_u64 v[4:5], v[4:5], 0, s[18:19]
	s_add_i32 m0, s23, 0x1a000
	s_add_i32 s49, s23, 0x8000
	s_add_i32 s53, s23, 0xa000
	v_bitop3_b32 v166, v15, s4, v14 bitop3:0xde
	global_load_lds_dwordx4 v[4:5], off
	v_lshl_add_u64 v[2:3], v[2:3], 0, s[18:19]
	s_mov_b32 m0, s49
	s_add_u32 s4, s26, 0x40080
	v_bitop3_b32 v17, v15, s5, v14 bitop3:0xde
	global_load_lds_dwordx4 v[2:3], off
	v_lshl_add_u64 v[0:1], v[0:1], 0, s[18:19]
	s_mov_b32 m0, s53
	s_addc_u32 s5, s27, 0
	global_load_lds_dwordx4 v[0:1], off
	s_add_i32 m0, s23, 0x1c000
	v_lshl_add_u64 v[0:1], s[4:5], 0, v[128:129]
	global_load_lds_dwordx4 v[0:1], off
	v_lshl_add_u64 v[0:1], s[4:5], 0, v[148:149]
	s_add_i32 m0, s23, 0x1e000
	s_mov_b32 s48, 0
	global_load_lds_dwordx4 v[0:1], off
	v_lshlrev_b32_e32 v0, 14, v12
	v_and_b32_e32 v0, 0xffff8000, v0
	v_lshl_add_u32 v0, v11, 11, v0
	v_and_b32_e32 v1, 1, v12
	v_lshl_or_b32 v0, v1, 6, v0
	v_lshl_add_u32 v154, v13, 1, v0
	v_lshlrev_b32_e32 v0, 14, v8
	v_and_b32_e32 v0, 0xffff8000, v0
	s_waitcnt vmcnt(10)
	s_barrier
	s_waitcnt vmcnt(6)
	v_lshl_add_u32 v0, v9, 11, v0
	v_and_b32_e32 v1, 1, v8
	v_lshl_or_b32 v0, v1, 6, v0
	v_or_b32_e32 v167, s6, v16
	v_mov_b32_e32 v155, v129
	v_lshl_add_u32 v156, v10, 1, v0
	v_mov_b32_e32 v157, v129
	v_add_u32_e32 v168, 0, v17
	s_barrier

; #define PG8_STAGE(bufoff, gbase, voff) do { _Pragma("unroll") for (int _i = 0; _i < 2; ++_i) \
;         __builtin_amdgcn_global_load_lds((const unsigned*)((const char*)(gbase) + (voff)[_i]), (PG8_LAS unsigned*)(lds + (bufoff) + ldsw + _i * 8192), 16, 0, 0); } while (0)
; #define PG8_WAIT_V(n) asm volatile("s_waitcnt vmcnt(" #n ")" ::: "memory")
; #define PG8_BAR __builtin_amdgcn_s_barrier()
;     __device__ bool next(int i, pg8::Unit& u) const { if (i != 0 || !valid) return false; u.pm = pm; u.pn = pn; return true; }
; template <class Epi, class Sched, bool STAMP = false>
; __device__ __forceinline__ void gemm_phase(PG8_LAS unsigned char* lds, const Gemm g, const Sched& S, const Epi& E, unsigned long long* stamps) {
;     ...
;     for (int i = 0; i < 2; ++i) { int R, C; stage_rc(tid * 16 + i * 8192, R, C); const int Rb = Epi::PERM ? ((R & ~31) + perm32(R & 31)) : R;
;         voffA[i] = (unsigned)(R * LD + C) * 2u; voffB[i] = (unsigned)(Rb * LD + C) * 2u; }
;     const size_t kstep = (size_t)(BK * 2);
;     const size_t hstep = (size_t)HALF * LD * 2;
;     const size_t tstep = 2 * hstep;
;     const unsigned ldsw = (unsigned)wid * 1024u;
;     const int aoff = lds_byte(wr * 64 + fr, fq * 8), boff = lds_byte(wc * 32 + fr, fq * 8);
;     ...
;     Unit cur, nxt; int ui = 0;
;     if (!S.next(0, cur)) return;
;     f32x4 acc[2][2][4][2];
; #pragma unroll
;     for (int a = 0; a < 2; ++a)
; #pragma unroll
;         for (int b = 0; b < 2; ++b)
; #pragma unroll
;             for (int m = 0; m < 4; ++m)
; #pragma unroll
;                 for (int n = 0; n < 2; ++n) acc[a][b][m][n] = (f32x4){0.f, 0.f, 0.f, 0.f};
;     bf16x8 At[4][2], B0[2][2], B1[2][2];
;     const char* cA = (const char*)g.A + (size_t)cur.pm * tstep; const char* cB = (const char*)g.Bt + (size_t)cur.pn * tstep;
;     S.a_ready(cur);
;     PG8_STAGE(PG8_SB(0, 0), cB, voffB); PG8_STAGE(PG8_SA(0, 0), cA, voffA); PG8_STAGE(PG8_SB(0, 1), cB + hstep, voffB); PG8_STAGE(PG8_SA(0, 1), cA + hstep, voffA);
;     if (wr == 1) PG8_BAR;
;     PG8_WAIT_V(4); PG8_BAR;
;     PG8_STAGE(PG8_SB(1, 0), cB + kstep, voffB); PG8_STAGE(PG8_SA(1, 0), cA + kstep, voffA); PG8_STAGE(PG8_SB(1, 1), cB + hstep + kstep, voffB);
;     PG8_WAIT_V(6); PG8_BAR;
.LBB0_1174:
	s_add_u32 s0, s10, 0x2200000
	s_addc_u32 s1, s42, 0
	s_and_b64 s[2:3], s[34:35], exec
	s_mov_b32 s2, 0x44000
	s_cselect_b32 s2, s2, 0x22000
	s_add_u32 s2, s10, s2
	s_addc_u32 s3, s42, 0
	v_bfe_u32 v17, v9, 4, 2
	s_add_u32 s2, s2, 0x2060000
	v_and_b32_e32 v18, 15, v9
	v_lshlrev_b32_e32 v19, 4, v17
	v_lshlrev_b32_e32 v9, 2, v9
	s_addc_u32 s3, s3, 0
	v_lshl_or_b32 v139, s4, 6, v18
	v_lshl_or_b32 v18, v18, 6, v19
	s_lshl_b32 s4, s4, 13
	v_and_b32_e32 v9, 32, v9
	v_bitop3_b32 v19, v18, s4, v9 bitop3:0xde
	s_lshl_b32 s4, s5, 5
	s_and_b32 s6, s4, 0x60
	s_add_i32 m0, s25, 0x18000
	v_lshl_add_u64 v[6:7], v[6:7], 0, s[18:19]
	s_lshl_b32 s4, s6, 7
	s_nop 0
	global_load_lds_dwordx4 v[6:7], off
	v_lshl_add_u64 v[4:5], v[4:5], 0, s[18:19]
	s_add_i32 m0, s25, 0x1a000
	s_add_i32 s59, s25, 0x8000
	s_add_i32 s60, s25, 0xa000
	v_bitop3_b32 v158, v18, s4, v9 bitop3:0xde
	global_load_lds_dwordx4 v[4:5], off
	v_lshl_add_u64 v[2:3], v[2:3], 0, s[18:19]
	s_mov_b32 m0, s59
	s_add_u32 s4, s30, 0x100080
	global_load_lds_dwordx4 v[2:3], off
	v_lshl_add_u64 v[0:1], v[0:1], 0, s[18:19]
	s_mov_b32 m0, s60
	s_addc_u32 s5, s31, 0
	global_load_lds_dwordx4 v[0:1], off
	s_add_i32 m0, s25, 0x1c000
	v_lshl_add_u64 v[0:1], s[4:5], 0, v[128:129]
	global_load_lds_dwordx4 v[0:1], off
	v_lshl_add_u64 v[0:1], s[4:5], 0, v[148:149]
	s_add_i32 m0, s25, 0x1e000
	s_mov_b64 s[4:5], 0x100080
	global_load_lds_dwordx4 v[0:1], off
	v_lshlrev_b32_e32 v0, 15, v8
	v_and_b32_e32 v0, 0x7fff0000, v0
	v_lshl_add_u32 v0, v10, 12, v0
	v_or_b32_e32 v0, v0, v11
	v_add_lshl_u32 v0, v0, v12, 1
	v_mov_b32_e32 v1, v129
	v_lshl_add_u64 v[150:151], v[0:1], 0, s[4:5]
	v_lshlrev_b32_e32 v0, 15, v13
	v_and_b32_e32 v0, 0x7fff0000, v0
	v_lshl_add_u32 v0, v14, 12, v0
	s_waitcnt vmcnt(10)
	s_barrier
	s_waitcnt vmcnt(6)
	v_or_b32_e32 v0, v0, v15
	v_add_lshl_u32 v0, v0, v16, 1
	s_mov_b32 s58, 0
	v_cmp_eq_u32_e64 s[38:39], 0, v17
	s_ashr_i32 s61, s43, 31
	v_lshl_or_b32 v159, v17, 2, s6
	v_lshl_add_u64 v[152:153], v[0:1], 0, s[4:5]
	v_add_u32_e32 v160, 0, v19
	s_barrier
	s_branch .LBB0_1176

; #define PG8_STAGE(bufoff, gbase, voff) do { _Pragma("unroll") for (int _i = 0; _i < 2; ++_i) \
;         __builtin_amdgcn_global_load_lds((const unsigned*)((const char*)(gbase) + (voff)[_i]), (PG8_LAS unsigned*)(lds + (bufoff) + ldsw + _i * 8192), 16, 0, 0); } while (0)
; #define PG8_WAIT_V(n) asm volatile("s_waitcnt vmcnt(" #n ")" ::: "memory")
; #define PG8_BAR __builtin_amdgcn_s_barrier()
; template <class Epi, class Sched, bool STAMP = false>
; __device__ __forceinline__ void gemm_phase(PG8_LAS unsigned char* lds, const Gemm g, const Sched& S, const Epi& E, unsigned long long* stamps) {
;     ...
;     f32x4 acc[2][2][4][2];
; #pragma unroll
;     for (int a = 0; a < 2; ++a)
; #pragma unroll
;         for (int b = 0; b < 2; ++b)
; #pragma unroll
;             for (int m = 0; m < 4; ++m)
; #pragma unroll
;                 for (int n = 0; n < 2; ++n) acc[a][b][m][n] = (f32x4){0.f, 0.f, 0.f, 0.f};
;     bf16x8 At[4][2], B0[2][2], B1[2][2];
;     const char* cA = (const char*)g.A + (size_t)cur.pm * tstep; const char* cB = (const char*)g.Bt + (size_t)cur.pn * tstep;
;     S.a_ready(cur);
;     PG8_STAGE(PG8_SB(0, 0), cB, voffB); PG8_STAGE(PG8_SA(0, 0), cA, voffA); PG8_STAGE(PG8_SB(0, 1), cB + hstep, voffB); PG8_STAGE(PG8_SA(0, 1), cA + hstep, voffA);
;     if (wr == 1) PG8_BAR;
;     PG8_WAIT_V(4); PG8_BAR;
;     PG8_STAGE(PG8_SB(1, 0), cB + kstep, voffB); PG8_STAGE(PG8_SA(1, 0), cA + kstep, voffA); PG8_STAGE(PG8_SB(1, 1), cB + hstep + kstep, voffB);
;     PG8_WAIT_V(6); PG8_BAR;
.LBB0_1206:
	v_bfe_u32 v139, v12, 4, 2
	s_lshl_b32 s6, s6, 5
	v_and_b32_e32 v154, 15, v12
	v_lshlrev_b32_e32 v17, 4, v139
	v_lshlrev_b32_e32 v12, 2, v12
	s_and_b32 s36, s6, 0x60
	s_add_i32 m0, s27, 0x18000
	v_lshl_add_u64 v[6:7], v[6:7], 0, s[18:19]
	s_lshl_b32 s35, s7, 6
	v_lshl_or_b32 v17, v154, 6, v17
	s_lshl_b32 s7, s7, 13
	v_and_b32_e32 v12, 32, v12
	s_lshl_b32 s6, s36, 7
	s_nop 0
	global_load_lds_dwordx4 v[6:7], off
	v_lshl_add_u64 v[4:5], v[4:5], 0, s[18:19]
	s_add_i32 m0, s27, 0x1a000
	s_add_i32 s37, s27, 0x8000
	s_add_i32 s38, s27, 0xa000
	v_bitop3_b32 v155, v17, s6, v12 bitop3:0xde
	global_load_lds_dwordx4 v[4:5], off
	v_lshl_add_u64 v[2:3], v[2:3], 0, s[18:19]
	s_mov_b32 m0, s37
	s_add_u32 s6, s0, 0x100080
	v_bitop3_b32 v18, v17, s7, v12 bitop3:0xde
	global_load_lds_dwordx4 v[2:3], off
	v_lshl_add_u64 v[0:1], v[0:1], 0, s[18:19]
	s_mov_b32 m0, s38
	s_addc_u32 s7, s1, 0
	global_load_lds_dwordx4 v[0:1], off
	s_add_i32 m0, s27, 0x1c000
	v_lshl_add_u64 v[0:1], s[6:7], 0, v[128:129]
	global_load_lds_dwordx4 v[0:1], off
	v_lshl_add_u64 v[0:1], s[6:7], 0, v[148:149]
	s_add_i32 m0, s27, 0x1e000
	s_lshl_b32 s4, s4, 16
	global_load_lds_dwordx4 v[0:1], off
	s_and_b32 s4, s4, 0x600000
	s_or_b32 s4, s4, s5
	v_lshlrev_b32_e32 v0, 15, v14
	v_and_b32_e32 v0, 0x7fff0000, v0
	s_add_u32 s4, s10, s4
	v_lshl_add_u32 v0, v13, 12, v0
	s_addc_u32 s5, s42, 0
	v_or_b32_e32 v0, v0, v15
	s_add_u32 s4, s4, 0xd600080
	v_add_lshl_u32 v0, v0, v16, 1
	v_mov_b32_e32 v1, v129
	s_addc_u32 s5, s5, 0
	v_lshl_add_u64 v[150:151], s[4:5], 0, v[0:1]
	v_lshlrev_b32_e32 v0, 15, v8
	v_and_b32_e32 v0, 0x7fff0000, v0
	v_lshl_add_u32 v0, v9, 12, v0
	v_or_b32_e32 v0, v0, v10
	s_waitcnt vmcnt(10)
	s_barrier
	s_waitcnt vmcnt(6)
	v_add_lshl_u32 v0, v0, v11, 1
	v_lshl_add_u64 v[152:153], s[4:5], 0, v[0:1]
	v_mov_b32_e32 v0, 0
	s_mov_b32 s39, -2
	s_mov_b64 s[4:5], 0
	v_add_u32_e32 v156, 0, v18
	v_mov_b32_e32 v1, v0
	v_mov_b32_e32 v2, v0
	v_mov_b32_e32 v3, v0
	v_mov_b32_e32 v4, v0
	v_mov_b32_e32 v5, v0
	v_mov_b32_e32 v6, v0
	v_mov_b32_e32 v7, v0
	v_mov_b32_e32 v8, v0
	v_mov_b32_e32 v9, v0
	v_mov_b32_e32 v10, v0
	v_mov_b32_e32 v11, v0
	v_mov_b32_e32 v12, v0
	v_mov_b32_e32 v13, v0
	v_mov_b32_e32 v14, v0
	v_mov_b32_e32 v15, v0
	v_mov_b32_e32 v24, v0
	v_mov_b32_e32 v25, v0
	v_mov_b32_e32 v26, v0
	v_mov_b32_e32 v27, v0
	v_mov_b32_e32 v28, v0
	v_mov_b32_e32 v29, v0
	v_mov_b32_e32 v30, v0
	v_mov_b32_e32 v31, v0
	v_mov_b32_e32 v40, v0
	v_mov_b32_e32 v41, v0
	v_mov_b32_e32 v42, v0
	v_mov_b32_e32 v43, v0
	v_mov_b32_e32 v44, v0
	v_mov_b32_e32 v45, v0
	v_mov_b32_e32 v46, v0
	v_mov_b32_e32 v47, v0
	v_mov_b32_e32 v16, v0
	v_mov_b32_e32 v17, v0
	v_mov_b32_e32 v18, v0
	v_mov_b32_e32 v19, v0
	v_mov_b32_e32 v20, v0
	v_mov_b32_e32 v21, v0
	v_mov_b32_e32 v22, v0
	v_mov_b32_e32 v23, v0
	v_mov_b32_e32 v32, v0
	v_mov_b32_e32 v33, v0
	v_mov_b32_e32 v34, v0
	v_mov_b32_e32 v35, v0
	v_mov_b32_e32 v36, v0
	v_mov_b32_e32 v37, v0
	v_mov_b32_e32 v38, v0
	v_mov_b32_e32 v39, v0
	v_mov_b32_e32 v48, v0
	v_mov_b32_e32 v49, v0
	v_mov_b32_e32 v50, v0
	v_mov_b32_e32 v51, v0
	v_mov_b32_e32 v52, v0
	v_mov_b32_e32 v53, v0
	v_mov_b32_e32 v54, v0
	v_mov_b32_e32 v55, v0
	v_mov_b32_e32 v56, v0
	v_mov_b32_e32 v57, v0
	v_mov_b32_e32 v58, v0
	v_mov_b32_e32 v59, v0
	v_mov_b32_e32 v60, v0
	v_mov_b32_e32 v61, v0
	v_mov_b32_e32 v62, v0
	v_mov_b32_e32 v63, v0
	v_mov_b32_e32 v64, v0
	v_mov_b32_e32 v65, v0
	v_mov_b32_e32 v66, v0
	v_mov_b32_e32 v67, v0
	v_mov_b32_e32 v68, v0
	v_mov_b32_e32 v69, v0
	v_mov_b32_e32 v70, v0
	v_mov_b32_e32 v71, v0
	v_mov_b32_e32 v72, v0
	v_mov_b32_e32 v73, v0
	v_mov_b32_e32 v74, v0
	v_mov_b32_e32 v75, v0
	v_mov_b32_e32 v76, v0
	v_mov_b32_e32 v77, v0
	v_mov_b32_e32 v78, v0
	s_waitcnt vmcnt(0)
	v_mov_b32_e32 v79, v0
	v_mov_b32_e32 v84, v0
	v_mov_b32_e32 v85, v0
	v_mov_b32_e32 v86, v0
	v_mov_b32_e32 v87, v0
	v_mov_b32_e32 v92, v0
	v_mov_b32_e32 v93, v0
	v_mov_b32_e32 v94, v0
	v_mov_b32_e32 v95, v0
	v_mov_b32_e32 v100, v0
	v_mov_b32_e32 v101, v0
	v_mov_b32_e32 v102, v0
	v_mov_b32_e32 v103, v0
	v_mov_b32_e32 v108, v0
	v_mov_b32_e32 v109, v0
	v_mov_b32_e32 v110, v0
	v_mov_b32_e32 v111, v0
	v_mov_b32_e32 v80, v0
	v_mov_b32_e32 v81, v0
	v_mov_b32_e32 v82, v0
	v_mov_b32_e32 v83, v0
	v_mov_b32_e32 v88, v0
	v_mov_b32_e32 v89, v0
	v_mov_b32_e32 v90, v0
	v_mov_b32_e32 v91, v0
	v_mov_b32_e32 v96, v0
	v_mov_b32_e32 v97, v0
	v_mov_b32_e32 v98, v0
	v_mov_b32_e32 v99, v0
	v_mov_b32_e32 v104, v0
	v_mov_b32_e32 v105, v0
	v_mov_b32_e32 v106, v0
	v_mov_b32_e32 v107, v0
	v_mov_b32_e32 v112, v0
	v_mov_b32_e32 v113, v0
	v_mov_b32_e32 v114, v0
	v_mov_b32_e32 v115, v0
	v_mov_b32_e32 v116, v0
	v_mov_b32_e32 v117, v0
	v_mov_b32_e32 v118, v0
	v_mov_b32_e32 v119, v0
	v_mov_b32_e32 v120, v0
	v_mov_b32_e32 v121, v0
	v_mov_b32_e32 v122, v0
	v_mov_b32_e32 v123, v0
	v_mov_b32_e32 v124, v0
	v_mov_b32_e32 v125, v0
	v_mov_b32_e32 v126, v0
	v_mov_b32_e32 v127, v0
	s_barrier

; #define PG8_STAGE(bufoff, gbase, voff) do { _Pragma("unroll") for (int _i = 0; _i < 2; ++_i) \
;         __builtin_amdgcn_global_load_lds((const unsigned*)((const char*)(gbase) + (voff)[_i]), (PG8_LAS unsigned*)(lds + (bufoff) + ldsw + _i * 8192), 16, 0, 0); } while (0)
; #define PG8_WAIT_V(n) asm volatile("s_waitcnt vmcnt(" #n ")" ::: "memory")
; #define PG8_BAR __builtin_amdgcn_s_barrier()
;     __device__ bool next(int i, pg8::Unit& u) const { if (i != 0 || !valid) return false; u.pm = pm; u.pn = pn; return true; }
; template <class Epi, class Sched, bool STAMP = false>
; __device__ __forceinline__ void gemm_phase(PG8_LAS unsigned char* lds, const Gemm g, const Sched& S, const Epi& E, unsigned long long* stamps) {
;     ...
;     for (int i = 0; i < 2; ++i) { int R, C; stage_rc(tid * 16 + i * 8192, R, C); const int Rb = Epi::PERM ? ((R & ~31) + perm32(R & 31)) : R;
;         voffA[i] = (unsigned)(R * LD + C) * 2u; voffB[i] = (unsigned)(Rb * LD + C) * 2u; }
;     const size_t kstep = (size_t)(BK * 2);
;     const size_t hstep = (size_t)HALF * LD * 2;
;     const size_t tstep = 2 * hstep;
;     const unsigned ldsw = (unsigned)wid * 1024u;
;     const int aoff = lds_byte(wr * 64 + fr, fq * 8), boff = lds_byte(wc * 32 + fr, fq * 8);
;     ...
;     Unit cur, nxt; int ui = 0;
;     if (!S.next(0, cur)) return;
;     f32x4 acc[2][2][4][2];
; #pragma unroll
;     for (int a = 0; a < 2; ++a)
; #pragma unroll
;         for (int b = 0; b < 2; ++b)
; #pragma unroll
;             for (int m = 0; m < 4; ++m)
; #pragma unroll
;                 for (int n = 0; n < 2; ++n) acc[a][b][m][n] = (f32x4){0.f, 0.f, 0.f, 0.f};
;     bf16x8 At[4][2], B0[2][2], B1[2][2];
;     const char* cA = (const char*)g.A + (size_t)cur.pm * tstep; const char* cB = (const char*)g.Bt + (size_t)cur.pn * tstep;
;     S.a_ready(cur);
;     PG8_STAGE(PG8_SB(0, 0), cB, voffB); PG8_STAGE(PG8_SA(0, 0), cA, voffA); PG8_STAGE(PG8_SB(0, 1), cB + hstep, voffB); PG8_STAGE(PG8_SA(0, 1), cA + hstep, voffA);
;     if (wr == 1) PG8_BAR;
;     PG8_WAIT_V(4); PG8_BAR;
;     PG8_STAGE(PG8_SB(1, 0), cB + kstep, voffB); PG8_STAGE(PG8_SA(1, 0), cA + kstep, voffA); PG8_STAGE(PG8_SB(1, 1), cB + hstep + kstep, voffB);
;     PG8_WAIT_V(6); PG8_BAR;
.LBB0_1336:
	v_lshl_add_u64 v[8:9], s[26:27], 0, v[128:129]
	v_mov_b32_e32 v149, v129
	s_lshl_b32 s6, s6, 5
	v_lshl_add_u64 v[10:11], s[26:27], 0, v[148:149]
	v_mov_b32_e32 v153, v129
	s_and_b32 s13, s6, 0x60
	s_add_i32 m0, s23, 0x18000
	v_lshl_add_u64 v[8:9], v[8:9], 0, s[18:19]
	v_lshl_add_u64 v[12:13], s[24:25], 0, v[152:153]
	v_mov_b32_e32 v151, v129
	s_lshl_b32 s12, s5, 13
	s_lshl_b32 s14, s13, 7
	s_nop 0
	global_load_lds_dwordx4 v[8:9], off
	v_lshl_add_u64 v[8:9], v[10:11], 0, s[18:19]
	s_add_i32 m0, s23, 0x1a000
	s_add_i32 s48, s23, 0x8000
	s_add_i32 s49, s23, 0xa000
	v_lshl_add_u64 v[14:15], s[24:25], 0, v[150:151]
	global_load_lds_dwordx4 v[8:9], off
	v_lshl_add_u64 v[8:9], v[12:13], 0, s[18:19]
	s_mov_b32 m0, s48
	s_add_u32 s6, s26, 0x40080
	global_load_lds_dwordx4 v[8:9], off
	v_lshl_add_u64 v[8:9], v[14:15], 0, s[18:19]
	s_mov_b32 m0, s49
	s_addc_u32 s7, s27, 0
	global_load_lds_dwordx4 v[8:9], off
	s_add_i32 m0, s23, 0x1c000
	v_lshl_add_u64 v[8:9], s[6:7], 0, v[128:129]
	global_load_lds_dwordx4 v[8:9], off
	v_lshl_add_u64 v[8:9], s[6:7], 0, v[148:149]
	s_add_i32 m0, s23, 0x1e000
	v_and_b32_e32 v7, 15, v0
	global_load_lds_dwordx4 v[8:9], off
	v_lshrrev_b32_e32 v8, 1, v0
	v_and_b32_e32 v8, 24, v8
	v_lshlrev_b32_e32 v9, 1, v8
	v_lshlrev_b32_e32 v0, 2, v0
	v_lshl_or_b32 v139, s5, 6, v7
	v_lshl_or_b32 v7, v7, 6, v9
	v_and_b32_e32 v0, 32, v0
	v_bitop3_b32 v9, v7, s12, v0 bitop3:0xde
	v_bitop3_b32 v166, v7, s14, v0 bitop3:0xde
	v_lshlrev_b32_e32 v0, 14, v5
	v_and_b32_e32 v0, 0xffff8000, v0
	v_lshl_add_u32 v0, v4, 11, v0
	v_and_b32_e32 v4, 1, v5
	v_lshl_or_b32 v0, v4, 6, v0
	v_lshl_add_u32 v154, v6, 1, v0
	v_lshlrev_b32_e32 v0, 14, v1
	v_and_b32_e32 v0, 0xffff8000, v0
	s_waitcnt vmcnt(10)
	s_barrier
	s_waitcnt vmcnt(6)
	v_lshl_add_u32 v0, v2, 11, v0
	v_and_b32_e32 v1, 1, v1
	v_lshl_or_b32 v0, v1, 6, v0
	s_sext_i32_i8 s56, s4
	v_or_b32_e32 v167, s13, v8
	v_mov_b32_e32 v155, v129
	v_lshl_add_u32 v156, v3, 1, v0
	v_mov_b32_e32 v157, v129
	s_mov_b32 s53, 0
	v_add_u32_e32 v168, 0, v9
	s_barrier

; #define PG8_STAGE(bufoff, gbase, voff) do { _Pragma("unroll") for (int _i = 0; _i < 2; ++_i) \
;         __builtin_amdgcn_global_load_lds((const unsigned*)((const char*)(gbase) + (voff)[_i]), (PG8_LAS unsigned*)(lds + (bufoff) + ldsw + _i * 8192), 16, 0, 0); } while (0)
; #define PG8_WAIT_V(n) asm volatile("s_waitcnt vmcnt(" #n ")" ::: "memory")
; #define PG8_BAR __builtin_amdgcn_s_barrier()
; template <class Epi, class Sched, bool STAMP = false>
; __device__ __forceinline__ void gemm_phase(PG8_LAS unsigned char* lds, const Gemm g, const Sched& S, const Epi& E, unsigned long long* stamps) {
;     ...
;     f32x4 acc[2][2][4][2];
; #pragma unroll
;     for (int a = 0; a < 2; ++a)
; #pragma unroll
;         for (int b = 0; b < 2; ++b)
; #pragma unroll
;             for (int m = 0; m < 4; ++m)
; #pragma unroll
;                 for (int n = 0; n < 2; ++n) acc[a][b][m][n] = (f32x4){0.f, 0.f, 0.f, 0.f};
;     bf16x8 At[4][2], B0[2][2], B1[2][2];
;     const char* cA = (const char*)g.A + (size_t)cur.pm * tstep; const char* cB = (const char*)g.Bt + (size_t)cur.pn * tstep;
;     S.a_ready(cur);
;     PG8_STAGE(PG8_SB(0, 0), cB, voffB); PG8_STAGE(PG8_SA(0, 0), cA, voffA); PG8_STAGE(PG8_SB(0, 1), cB + hstep, voffB); PG8_STAGE(PG8_SA(0, 1), cA + hstep, voffA);
;     if (wr == 1) PG8_BAR;
;     PG8_WAIT_V(4); PG8_BAR;
;     PG8_STAGE(PG8_SB(1, 0), cB + kstep, voffB); PG8_STAGE(PG8_SA(1, 0), cA + kstep, voffA); PG8_STAGE(PG8_SB(1, 1), cB + hstep + kstep, voffB);
;     PG8_WAIT_V(6); PG8_BAR;
.LBB0_1348:
	v_bfe_u32 v139, v0, 4, 2
	s_lshl_b32 s14, s14, 5
	v_and_b32_e32 v150, 15, v0
	v_lshlrev_b32_e32 v1, 4, v139
	v_lshlrev_b32_e32 v0, 2, v0
	s_and_b32 s56, s14, 0x60
	v_lshl_add_u64 v[2:3], s[6:7], 0, v[128:129]
	v_mov_b32_e32 v149, v129
	s_lshl_b32 s53, s15, 6
	v_lshl_or_b32 v1, v150, 6, v1
	s_lshl_b32 s15, s15, 13
	v_and_b32_e32 v0, 32, v0
	s_lshl_b32 s14, s56, 7
	v_lshl_add_u64 v[4:5], s[6:7], 0, v[148:149]
	v_bitop3_b32 v10, v1, s15, v0 bitop3:0xde
	v_bitop3_b32 v151, v1, s14, v0 bitop3:0xde
	s_add_i32 m0, s10, 0x18000
	v_lshl_add_u64 v[0:1], v[2:3], 0, s[18:19]
	v_lshl_add_u64 v[6:7], s[12:13], 0, v[128:129]
	s_nop 0
	global_load_lds_dwordx4 v[0:1], off
	v_lshl_add_u64 v[0:1], v[4:5], 0, s[18:19]
	s_add_i32 m0, s10, 0x1a000
	s_add_i32 s57, s10, 0x8000
	s_add_i32 s58, s10, 0xa000
	v_lshl_add_u64 v[8:9], s[12:13], 0, v[148:149]
	global_load_lds_dwordx4 v[0:1], off
	v_lshl_add_u64 v[0:1], v[6:7], 0, s[18:19]
	s_mov_b32 m0, s57
	s_add_u32 s14, s6, 0x40080
	global_load_lds_dwordx4 v[0:1], off
	v_lshl_add_u64 v[0:1], v[8:9], 0, s[18:19]
	s_mov_b32 m0, s58
	s_addc_u32 s15, s7, 0
	global_load_lds_dwordx4 v[0:1], off
	s_add_i32 m0, s10, 0x1c000
	v_lshl_add_u64 v[0:1], s[14:15], 0, v[128:129]
	global_load_lds_dwordx4 v[0:1], off
	v_lshl_add_u64 v[0:1], s[14:15], 0, v[148:149]
	s_add_i32 m0, s10, 0x1e000
	s_mov_b32 s14, 0
	global_load_lds_dwordx4 v[0:1], off
	s_waitcnt vmcnt(10)
	s_barrier
	s_waitcnt vmcnt(6)
	v_mov_b32_e32 v0, 0
	s_mov_b64 s[22:23], -1
	s_mov_b64 s[24:25], 0
	v_add_u32_e32 v152, 0, v10
	v_mov_b32_e32 v1, v0
	v_mov_b32_e32 v2, v0
	v_mov_b32_e32 v3, v0
	v_mov_b32_e32 v4, v0
	v_mov_b32_e32 v5, v0
	v_mov_b32_e32 v6, v0
	v_mov_b32_e32 v7, v0
	v_mov_b32_e32 v8, v0
	v_mov_b32_e32 v9, v0
	v_mov_b32_e32 v10, v0
	v_mov_b32_e32 v11, v0
	v_mov_b32_e32 v12, v0
	v_mov_b32_e32 v13, v0
	v_mov_b32_e32 v14, v0
	v_mov_b32_e32 v15, v0
	v_mov_b32_e32 v24, v0
	v_mov_b32_e32 v25, v0
	v_mov_b32_e32 v26, v0
	v_mov_b32_e32 v27, v0
	v_mov_b32_e32 v28, v0
	v_mov_b32_e32 v29, v0
	v_mov_b32_e32 v30, v0
	v_mov_b32_e32 v31, v0
	v_mov_b32_e32 v40, v0
	v_mov_b32_e32 v41, v0
	v_mov_b32_e32 v42, v0
	v_mov_b32_e32 v43, v0
	v_mov_b32_e32 v44, v0
	v_mov_b32_e32 v45, v0
	v_mov_b32_e32 v46, v0
	v_mov_b32_e32 v47, v0
	v_mov_b32_e32 v16, v0
	v_mov_b32_e32 v17, v0
	v_mov_b32_e32 v18, v0
	v_mov_b32_e32 v19, v0
	v_mov_b32_e32 v20, v0
	v_mov_b32_e32 v21, v0
	v_mov_b32_e32 v22, v0
	v_mov_b32_e32 v23, v0
	v_mov_b32_e32 v32, v0
	v_mov_b32_e32 v33, v0
	v_mov_b32_e32 v34, v0
	v_mov_b32_e32 v35, v0
	v_mov_b32_e32 v36, v0
	v_mov_b32_e32 v37, v0
	v_mov_b32_e32 v38, v0
	v_mov_b32_e32 v39, v0
	v_mov_b32_e32 v48, v0
	v_mov_b32_e32 v49, v0
	v_mov_b32_e32 v50, v0
	v_mov_b32_e32 v51, v0
	v_mov_b32_e32 v52, v0
	v_mov_b32_e32 v53, v0
	v_mov_b32_e32 v54, v0
	v_mov_b32_e32 v55, v0
	v_mov_b32_e32 v56, v0
	v_mov_b32_e32 v57, v0
	v_mov_b32_e32 v58, v0
	v_mov_b32_e32 v59, v0
	v_mov_b32_e32 v60, v0
	v_mov_b32_e32 v61, v0
	v_mov_b32_e32 v62, v0
	v_mov_b32_e32 v63, v0
	v_mov_b32_e32 v64, v0
	v_mov_b32_e32 v65, v0
	v_mov_b32_e32 v66, v0
	v_mov_b32_e32 v67, v0
	v_mov_b32_e32 v68, v0
	v_mov_b32_e32 v69, v0
	v_mov_b32_e32 v70, v0
	v_mov_b32_e32 v71, v0
	v_mov_b32_e32 v72, v0
	v_mov_b32_e32 v73, v0
	v_mov_b32_e32 v74, v0
	v_mov_b32_e32 v75, v0
	v_mov_b32_e32 v76, v0
	v_mov_b32_e32 v77, v0
	v_mov_b32_e32 v78, v0
	s_waitcnt vmcnt(0)
	v_mov_b32_e32 v79, v0
	v_mov_b32_e32 v84, v0
	v_mov_b32_e32 v85, v0
	v_mov_b32_e32 v86, v0
	v_mov_b32_e32 v87, v0
	v_mov_b32_e32 v92, v0
	v_mov_b32_e32 v93, v0
	v_mov_b32_e32 v94, v0
	v_mov_b32_e32 v95, v0
	v_mov_b32_e32 v100, v0
	v_mov_b32_e32 v101, v0
	v_mov_b32_e32 v102, v0
	v_mov_b32_e32 v103, v0
	v_mov_b32_e32 v108, v0
	v_mov_b32_e32 v109, v0
	v_mov_b32_e32 v110, v0
	v_mov_b32_e32 v111, v0
	v_mov_b32_e32 v80, v0
	v_mov_b32_e32 v81, v0
	v_mov_b32_e32 v82, v0
	v_mov_b32_e32 v83, v0
	v_mov_b32_e32 v88, v0
	v_mov_b32_e32 v89, v0
	v_mov_b32_e32 v90, v0
	v_mov_b32_e32 v91, v0
	v_mov_b32_e32 v96, v0
	v_mov_b32_e32 v97, v0
	v_mov_b32_e32 v98, v0
	v_mov_b32_e32 v99, v0
	v_mov_b32_e32 v104, v0
	v_mov_b32_e32 v105, v0
	v_mov_b32_e32 v106, v0
	v_mov_b32_e32 v107, v0
	v_mov_b32_e32 v112, v0
	v_mov_b32_e32 v113, v0
	v_mov_b32_e32 v114, v0
	v_mov_b32_e32 v115, v0
	v_mov_b32_e32 v116, v0
	v_mov_b32_e32 v117, v0
	v_mov_b32_e32 v118, v0
	v_mov_b32_e32 v119, v0
	v_mov_b32_e32 v120, v0
	v_mov_b32_e32 v121, v0
	v_mov_b32_e32 v122, v0
	v_mov_b32_e32 v123, v0
	v_mov_b32_e32 v124, v0
	v_mov_b32_e32 v125, v0
	v_mov_b32_e32 v126, v0
	v_mov_b32_e32 v127, v0
	s_barrier
